# chain order walking along n first (12 SrcB-sharing boundaries + 3 SrcA-sharing per segment) instead of the alternating snake
# baseline (speedup 1.0000x reference)
; #define PG8_STAGE(bufoff, gbase, voff) do { _Pragma("unroll") for (int _i = 0; _i < 2; ++_i) \
;         __builtin_amdgcn_global_load_lds((const unsigned*)((const char*)(gbase) + (voff)[_i]), (PG8_LAS unsigned*)(lds + (bufoff) + ldsw + _i * 8192), 16, 0, 0); } while (0)
; #define PG8_LDA(dst, b, h) do { _Pragma("unroll") for (int m = 0; m < 4; ++m) _Pragma("unroll") for (int k = 0; k < 2; ++k) dst[m][k] = *(const PG8_LAS bf16x8*)(lds + PG8_SA(b, h) + aoff + m * 2048 + k * 1024); } while (0)
; #define PG8_LDB(dst, b, h) do { _Pragma("unroll") for (int n = 0; n < 2; ++n) _Pragma("unroll") for (int k = 0; k < 2; ++k) dst[n][k] = *(const PG8_LAS bf16x8*)(lds + PG8_SB(b, h) + boff + n * 2048 + k * 1024); } while (0)
; #define PG8_MMA(ai, bj, At, Bt) do { __builtin_amdgcn_s_setprio(1); _Pragma("unroll") for (int m = 0; m < 4; ++m) _Pragma("unroll") for (int n = 0; n < 2; ++n) _Pragma("unroll") for (int k = 0; k < 2; ++k) \
;         acc[ai][bj][m][n] = __builtin_amdgcn_mfma_f32_16x16x32_bf16(Bt[n][k], At[m][k], acc[ai][bj][m][n], 0, 0, 0); __builtin_amdgcn_s_setprio(0); } while (0)
; #define PG8_WAIT_V(n) asm volatile("s_waitcnt vmcnt(" #n ")" ::: "memory")
; #define PG8_BAR __builtin_amdgcn_s_barrier()
; template <class Epi, class Sched, bool ALIGN_EPI = false, bool SP2 = false, bool ABLK = false, bool BBLK = false>
; __device__ __forceinline__ void gemm_phase(PG8_LAS unsigned char* lds, const Gemm g, const Sched& S, const Epi& E) {
;     ...
;             const bool last = (t == nt - 2);
;             const char* a1 = cA + (size_t)(t + 1) * kstepA;
;             const char* a2 = last ? nA : cA + (size_t)(t + 2) * kstepA; const char* b2 = last ? nB : cB + (size_t)(t + 2) * kstepB;
;             const char* a3 = a2 + kstepA; const char* b3 = b2 + kstepB;
;             if (last && has_next) S.a_ready(nxt);
;             if constexpr (SP2) {
;             PG8_LDB(B0, 0, 0); PG8_LDB(B1, 0, 1); PG8_SCHED; PG8_LDA(At, 0, 0); PG8_STAGE(PG8_SA(1, 1), a1 + hstepA, voffA);
;             PG8_WAIT_V(8); PG8_WAIT_L(0); PG8_BAR; PG8_MMA(0, 0, At, B0); PG8_MMA(0, 1, At, B1); PG8_BAR; PG8_SCHED;
;             PG8_LDA(At, 0, 1); PG8_STAGE(PG8_SB(0, 0), b2, voffB); PG8_STAGE(PG8_SB(0, 1), b2 + hstepB, voffB); PG8_STAGE(PG8_SA(0, 0), a2, voffA);
;             PG8_WAIT_V(8); PG8_WAIT_L(0); PG8_BAR; PG8_MMA(1, 0, At, B0); PG8_MMA(1, 1, At, B1); PG8_BAR; PG8_SCHED;
.LBB0_185:
	s_add_u32 s13, s20, 0x4000
	s_addc_u32 s22, s21, 0
	s_cmp_eq_u32 vcc_hi, 28
	s_cselect_b32 s26, s70, s13
	s_cselect_b32 s27, s9, s22
	s_cselect_b32 s24, s71, s77
	s_cselect_b32 s25, s7, vcc_lo
	s_add_u32 s22, s26, 0x8000
	s_addc_u32 s23, s27, 0
	s_add_i32 s13, 0, 0x10000
	v_add_u32_e32 v36, s13, v160
	s_add_i32 s88, 0, 0x14000
	ds_read_b128 v[152:155], v36
	ds_read_b128 v[156:159], v36 offset:1024
	ds_read_b128 v[162:165], v36 offset:2048
	ds_read_b128 v[166:169], v36 offset:3072
	v_add_u32_e32 v36, s88, v160
	ds_read_b128 v[170:173], v36
	ds_read_b128 v[174:177], v36 offset:1024
	ds_read_b128 v[178:181], v36 offset:2048
	ds_read_b128 v[182:185], v36 offset:3072
	s_add_i32 m0, s19, 0xc000
	ds_read_b128 v[186:189], v161
	ds_read_b128 v[190:193], v161 offset:1024
	ds_read_b128 v[194:197], v161 offset:2048
	ds_read_b128 v[198:201], v161 offset:3072
	ds_read_b128 v[202:205], v161 offset:4096
	ds_read_b128 v[206:209], v161 offset:5120
	ds_read_b128 v[210:213], v161 offset:6144
	ds_read_b128 v[214:217], v161 offset:7168
	global_load_lds_dwordx4 v148, s[20:21]
	s_add_i32 m0, s19, 0xe000
	s_nop 0
	global_load_lds_dwordx4 v150, s[20:21]
	s_waitcnt vmcnt(8)
	s_waitcnt lgkmcnt(0)
	v_mfma_f32_16x16x32_bf16 v[132:135], v[152:155], v[186:189], v[132:135]
	v_mfma_f32_16x16x32_bf16 v[132:135], v[156:159], v[190:193], v[132:135]
	v_mfma_f32_16x16x32_bf16 v[128:131], v[166:169], v[190:193], v[128:131]
	v_mfma_f32_16x16x32_bf16 v[128:131], v[162:165], v[186:189], v[128:131]
	s_barrier
	s_setprio 1
	v_mfma_f32_16x16x32_bf16 v[124:127], v[170:173], v[186:189], v[124:127]
	v_mfma_f32_16x16x32_bf16 v[124:127], v[174:177], v[190:193], v[124:127]
	v_mfma_f32_16x16x32_bf16 v[120:123], v[182:185], v[190:193], v[120:123]
	v_mfma_f32_16x16x32_bf16 v[120:123], v[178:181], v[186:189], v[120:123]
	v_mfma_f32_16x16x32_bf16 v[104:107], v[178:181], v[194:197], v[104:107]
	v_mfma_f32_16x16x32_bf16 v[104:107], v[182:185], v[198:201], v[104:107]
	v_mfma_f32_16x16x32_bf16 v[116:119], v[156:159], v[198:201], v[116:119]
	v_mfma_f32_16x16x32_bf16 v[116:119], v[152:155], v[194:197], v[116:119]
	v_mfma_f32_16x16x32_bf16 v[112:115], v[162:165], v[194:197], v[112:115]
	v_mfma_f32_16x16x32_bf16 v[112:115], v[166:169], v[198:201], v[112:115]
	v_mfma_f32_16x16x32_bf16 v[108:111], v[174:177], v[198:201], v[108:111]
	v_mfma_f32_16x16x32_bf16 v[108:111], v[170:173], v[194:197], v[108:111]
	s_setprio 0
	s_setprio 1
	v_mfma_f32_16x16x32_bf16 v[92:95], v[170:173], v[202:205], v[92:95]
	v_mfma_f32_16x16x32_bf16 v[92:95], v[174:177], v[206:209], v[92:95]
	v_mfma_f32_16x16x32_bf16 v[100:103], v[156:159], v[206:209], v[100:103]
	v_mfma_f32_16x16x32_bf16 v[100:103], v[152:155], v[202:205], v[100:103]
	v_mfma_f32_16x16x32_bf16 v[96:99], v[162:165], v[202:205], v[96:99]
	v_mfma_f32_16x16x32_bf16 v[96:99], v[166:169], v[206:209], v[96:99]
	v_mfma_f32_16x16x32_bf16 v[88:91], v[182:185], v[206:209], v[88:91]
	v_mfma_f32_16x16x32_bf16 v[88:91], v[178:181], v[202:205], v[88:91]
	v_mfma_f32_16x16x32_bf16 v[72:75], v[178:181], v[210:213], v[72:75]
	v_mfma_f32_16x16x32_bf16 v[72:75], v[182:185], v[214:217], v[72:75]
	v_mfma_f32_16x16x32_bf16 v[84:87], v[156:159], v[214:217], v[84:87]
	v_mfma_f32_16x16x32_bf16 v[84:87], v[152:155], v[210:213], v[84:87]
	v_mfma_f32_16x16x32_bf16 v[80:83], v[162:165], v[210:213], v[80:83]
	v_mfma_f32_16x16x32_bf16 v[80:83], v[166:169], v[214:217], v[80:83]
	v_mfma_f32_16x16x32_bf16 v[76:79], v[174:177], v[214:217], v[76:79]
	v_mfma_f32_16x16x32_bf16 v[76:79], v[170:173], v[210:213], v[76:79]
	s_setprio 0
	s_barrier
	s_add_i32 s13, s13, s31
	s_mov_b32 m0, s13
	ds_read_b128 v[186:189], v161 offset:16384
	ds_read_b128 v[190:193], v161 offset:17408
	ds_read_b128 v[194:197], v161 offset:18432
	ds_read_b128 v[198:201], v161 offset:19456
	ds_read_b128 v[202:205], v161 offset:20480
	ds_read_b128 v[206:209], v161 offset:21504
	ds_read_b128 v[210:213], v161 offset:22528
	ds_read_b128 v[214:217], v161 offset:23552
	global_load_lds_dwordx4 v140, s[24:25]
	s_add_i32 m0, s13, 0x2000
	s_add_u32 s68, s24, 0x4000
	s_addc_u32 s69, s25, 0
	s_add_i32 s13, s88, s31
	global_load_lds_dwordx4 v136, s[24:25]
	s_mov_b32 m0, s13
	s_nop 0
	global_load_lds_dwordx4 v140, s[68:69]
	s_add_i32 m0, s13, 0x2000
	s_nop 0
	global_load_lds_dwordx4 v136, s[68:69]
	s_mov_b32 m0, s19
	s_nop 0
	global_load_lds_dwordx4 v142, s[26:27]
	s_mov_b32 m0, s35
	s_nop 0
	global_load_lds_dwordx4 v138, s[26:27]
	s_waitcnt vmcnt(8)
	s_waitcnt lgkmcnt(0)
	v_mfma_f32_16x16x32_bf16 v[68:71], v[152:155], v[186:189], v[68:71]
	v_mfma_f32_16x16x32_bf16 v[68:71], v[156:159], v[190:193], v[68:71]
	v_mfma_f32_16x16x32_bf16 v[64:67], v[166:169], v[190:193], v[64:67]
	v_mfma_f32_16x16x32_bf16 v[64:67], v[162:165], v[186:189], v[64:67]
	s_barrier
; #define PG8_STAGE(bufoff, gbase, voff) do { _Pragma("unroll") for (int _i = 0; _i < 2; ++_i) \
;         __builtin_amdgcn_global_load_lds((const unsigned*)((const char*)(gbase) + (voff)[_i]), (PG8_LAS unsigned*)(lds + (bufoff) + ldsw + _i * 8192), 16, 0, 0); } while (0)
; #define PG8_LDA(dst, b, h) do { _Pragma("unroll") for (int m = 0; m < 4; ++m) _Pragma("unroll") for (int k = 0; k < 2; ++k) dst[m][k] = *(const PG8_LAS bf16x8*)(lds + PG8_SA(b, h) + aoff + m * 2048 + k * 1024); } while (0)
; #define PG8_LDB(dst, b, h) do { _Pragma("unroll") for (int n = 0; n < 2; ++n) _Pragma("unroll") for (int k = 0; k < 2; ++k) dst[n][k] = *(const PG8_LAS bf16x8*)(lds + PG8_SB(b, h) + boff + n * 2048 + k * 1024); } while (0)
; #define PG8_MMA(ai, bj, At, Bt) do { __builtin_amdgcn_s_setprio(1); _Pragma("unroll") for (int m = 0; m < 4; ++m) _Pragma("unroll") for (int n = 0; n < 2; ++n) _Pragma("unroll") for (int k = 0; k < 2; ++k) \
;         acc[ai][bj][m][n] = __builtin_amdgcn_mfma_f32_16x16x32_bf16(Bt[n][k], At[m][k], acc[ai][bj][m][n], 0, 0, 0); __builtin_amdgcn_s_setprio(0); } while (0)
; #define PG8_WAIT_V(n) asm volatile("s_waitcnt vmcnt(" #n ")" ::: "memory")
; #define PG8_WAIT_L(n) asm volatile("s_waitcnt lgkmcnt(" #n ")" ::: "memory")
; #define PG8_BAR __builtin_amdgcn_s_barrier()
; #define PG8_SCHED __builtin_amdgcn_sched_barrier(0)
; template <class Epi, class Sched, bool ALIGN_EPI = false, bool SP2 = false, bool ABLK = false, bool BBLK = false>
; __device__ __forceinline__ void gemm_phase(PG8_LAS unsigned char* lds, const Gemm g, const Sched& S, const Epi& E) {
;     ...
;             PG8_WAIT_V(8); PG8_WAIT_L(0); PG8_BAR; PG8_MMA(1, 0, At, B0); PG8_MMA(1, 1, At, B1); PG8_BAR; PG8_SCHED;
;             PG8_LDB(B0, 1, 0); PG8_LDB(B1, 1, 1); PG8_SCHED; PG8_LDA(At, 1, 0); PG8_STAGE(PG8_SA(0, 1), a2 + hstepA, voffA);
;             PG8_WAIT_V(8); PG8_WAIT_L(0); PG8_BAR; PG8_MMA(0, 0, At, B0); PG8_MMA(0, 1, At, B1); PG8_BAR; PG8_SCHED;
	s_setprio 1
	v_mfma_f32_16x16x32_bf16 v[60:63], v[170:173], v[186:189], v[60:63]
	v_mfma_f32_16x16x32_bf16 v[60:63], v[174:177], v[190:193], v[60:63]
	v_mfma_f32_16x16x32_bf16 v[56:59], v[182:185], v[190:193], v[56:59]
	v_mfma_f32_16x16x32_bf16 v[56:59], v[178:181], v[186:189], v[56:59]
	v_mfma_f32_16x16x32_bf16 v[40:43], v[178:181], v[194:197], v[40:43]
	v_mfma_f32_16x16x32_bf16 v[40:43], v[182:185], v[198:201], v[40:43]
	v_mfma_f32_16x16x32_bf16 v[52:55], v[156:159], v[198:201], v[52:55]
	v_mfma_f32_16x16x32_bf16 v[52:55], v[152:155], v[194:197], v[52:55]
	v_mfma_f32_16x16x32_bf16 v[48:51], v[162:165], v[194:197], v[48:51]
	v_mfma_f32_16x16x32_bf16 v[48:51], v[166:169], v[198:201], v[48:51]
	v_mfma_f32_16x16x32_bf16 v[44:47], v[174:177], v[198:201], v[44:47]
	v_mfma_f32_16x16x32_bf16 v[44:47], v[170:173], v[194:197], v[44:47]
	s_setprio 0
	s_setprio 1
	v_mfma_f32_16x16x32_bf16 v[24:27], v[170:173], v[202:205], v[24:27]
	v_mfma_f32_16x16x32_bf16 v[24:27], v[174:177], v[206:209], v[24:27]
	v_mfma_f32_16x16x32_bf16 v[32:35], v[156:159], v[206:209], v[32:35]
	v_mfma_f32_16x16x32_bf16 v[32:35], v[152:155], v[202:205], v[32:35]
	v_mfma_f32_16x16x32_bf16 v[28:31], v[162:165], v[202:205], v[28:31]
	v_mfma_f32_16x16x32_bf16 v[28:31], v[166:169], v[206:209], v[28:31]
	v_mfma_f32_16x16x32_bf16 v[20:23], v[182:185], v[206:209], v[20:23]
	v_mfma_f32_16x16x32_bf16 v[20:23], v[178:181], v[202:205], v[20:23]
	v_mfma_f32_16x16x32_bf16 v[4:7], v[178:181], v[210:213], v[4:7]
	v_mfma_f32_16x16x32_bf16 v[4:7], v[182:185], v[214:217], v[4:7]
	v_mfma_f32_16x16x32_bf16 v[16:19], v[156:159], v[214:217], v[16:19]
	v_mfma_f32_16x16x32_bf16 v[16:19], v[152:155], v[210:213], v[16:19]
	v_mfma_f32_16x16x32_bf16 v[12:15], v[162:165], v[210:213], v[12:15]
	v_mfma_f32_16x16x32_bf16 v[12:15], v[166:169], v[214:217], v[12:15]
	v_mfma_f32_16x16x32_bf16 v[8:11], v[174:177], v[214:217], v[8:11]
	v_mfma_f32_16x16x32_bf16 v[8:11], v[170:173], v[210:213], v[8:11]
	s_setprio 0
	s_barrier
	s_add_i32 s13, 0, 0x18000
	v_add_u32_e32 v36, s13, v160
	s_add_i32 s68, 0, 0x1c000
	ds_read_b128 v[152:155], v36
	ds_read_b128 v[156:159], v36 offset:1024
	ds_read_b128 v[162:165], v36 offset:2048
	ds_read_b128 v[166:169], v36 offset:3072
	v_add_u32_e32 v36, s68, v160
	ds_read_b128 v[170:173], v36
	ds_read_b128 v[174:177], v36 offset:1024
	ds_read_b128 v[178:181], v36 offset:2048
	ds_read_b128 v[182:185], v36 offset:3072
	s_add_u32 s26, s26, 0x4000
	s_addc_u32 s27, s27, 0
	s_mov_b32 m0, s36
	ds_read_b128 v[186:189], v161 offset:32768
	ds_read_b128 v[190:193], v161 offset:33792
	ds_read_b128 v[194:197], v161 offset:34816
	ds_read_b128 v[198:201], v161 offset:35840
	ds_read_b128 v[202:205], v161 offset:36864
	ds_read_b128 v[206:209], v161 offset:37888
	ds_read_b128 v[210:213], v161 offset:38912
	ds_read_b128 v[214:217], v161 offset:39936
	global_load_lds_dwordx4 v142, s[26:27]
	s_mov_b32 m0, s37
	s_nop 0
	global_load_lds_dwordx4 v138, s[26:27]
	s_waitcnt vmcnt(8)
	s_waitcnt lgkmcnt(0)
	v_mfma_f32_16x16x32_bf16 v[132:135], v[152:155], v[186:189], v[132:135]
	v_mfma_f32_16x16x32_bf16 v[132:135], v[156:159], v[190:193], v[132:135]
	v_mfma_f32_16x16x32_bf16 v[128:131], v[166:169], v[190:193], v[128:131]
	v_mfma_f32_16x16x32_bf16 v[128:131], v[162:165], v[186:189], v[128:131]
	s_barrier
	s_setprio 1
	v_mfma_f32_16x16x32_bf16 v[124:127], v[170:173], v[186:189], v[124:127]
	v_mfma_f32_16x16x32_bf16 v[124:127], v[174:177], v[190:193], v[124:127]
	v_mfma_f32_16x16x32_bf16 v[120:123], v[182:185], v[190:193], v[120:123]
	v_mfma_f32_16x16x32_bf16 v[120:123], v[178:181], v[186:189], v[120:123]
	v_mfma_f32_16x16x32_bf16 v[104:107], v[178:181], v[194:197], v[104:107]
	v_mfma_f32_16x16x32_bf16 v[104:107], v[182:185], v[198:201], v[104:107]
	v_mfma_f32_16x16x32_bf16 v[116:119], v[156:159], v[198:201], v[116:119]
	v_mfma_f32_16x16x32_bf16 v[116:119], v[152:155], v[194:197], v[116:119]
	v_mfma_f32_16x16x32_bf16 v[112:115], v[162:165], v[194:197], v[112:115]
	v_mfma_f32_16x16x32_bf16 v[112:115], v[166:169], v[198:201], v[112:115]
	v_mfma_f32_16x16x32_bf16 v[108:111], v[174:177], v[198:201], v[108:111]
	v_mfma_f32_16x16x32_bf16 v[108:111], v[170:173], v[194:197], v[108:111]
	s_setprio 0
	s_setprio 1
	v_mfma_f32_16x16x32_bf16 v[92:95], v[170:173], v[202:205], v[92:95]
	v_mfma_f32_16x16x32_bf16 v[92:95], v[174:177], v[206:209], v[92:95]
	v_mfma_f32_16x16x32_bf16 v[100:103], v[156:159], v[206:209], v[100:103]
	v_mfma_f32_16x16x32_bf16 v[100:103], v[152:155], v[202:205], v[100:103]
	v_mfma_f32_16x16x32_bf16 v[96:99], v[162:165], v[202:205], v[96:99]
	v_mfma_f32_16x16x32_bf16 v[96:99], v[166:169], v[206:209], v[96:99]
	v_mfma_f32_16x16x32_bf16 v[88:91], v[182:185], v[206:209], v[88:91]
	v_mfma_f32_16x16x32_bf16 v[88:91], v[178:181], v[202:205], v[88:91]
	v_mfma_f32_16x16x32_bf16 v[72:75], v[178:181], v[210:213], v[72:75]
	v_mfma_f32_16x16x32_bf16 v[72:75], v[182:185], v[214:217], v[72:75]
	v_mfma_f32_16x16x32_bf16 v[84:87], v[156:159], v[214:217], v[84:87]
	v_mfma_f32_16x16x32_bf16 v[84:87], v[152:155], v[210:213], v[84:87]
	v_mfma_f32_16x16x32_bf16 v[80:83], v[162:165], v[210:213], v[80:83]
	v_mfma_f32_16x16x32_bf16 v[80:83], v[166:169], v[214:217], v[80:83]
	v_mfma_f32_16x16x32_bf16 v[76:79], v[174:177], v[214:217], v[76:79]
	v_mfma_f32_16x16x32_bf16 v[76:79], v[170:173], v[210:213], v[76:79]
	s_setprio 0
	s_barrier
; #define PG8_STAGE(bufoff, gbase, voff) do { _Pragma("unroll") for (int _i = 0; _i < 2; ++_i) \
;         __builtin_amdgcn_global_load_lds((const unsigned*)((const char*)(gbase) + (voff)[_i]), (PG8_LAS unsigned*)(lds + (bufoff) + ldsw + _i * 8192), 16, 0, 0); } while (0)
; #define PG8_LDA(dst, b, h) do { _Pragma("unroll") for (int m = 0; m < 4; ++m) _Pragma("unroll") for (int k = 0; k < 2; ++k) dst[m][k] = *(const PG8_LAS bf16x8*)(lds + PG8_SA(b, h) + aoff + m * 2048 + k * 1024); } while (0)
; #define PG8_MMA(ai, bj, At, Bt) do { __builtin_amdgcn_s_setprio(1); _Pragma("unroll") for (int m = 0; m < 4; ++m) _Pragma("unroll") for (int n = 0; n < 2; ++n) _Pragma("unroll") for (int k = 0; k < 2; ++k) \
;         acc[ai][bj][m][n] = __builtin_amdgcn_mfma_f32_16x16x32_bf16(Bt[n][k], At[m][k], acc[ai][bj][m][n], 0, 0, 0); __builtin_amdgcn_s_setprio(0); } while (0)
; #define PG8_WAIT_V(n) asm volatile("s_waitcnt vmcnt(" #n ")" ::: "memory")
; #define PG8_WAIT_L(n) asm volatile("s_waitcnt lgkmcnt(" #n ")" ::: "memory")
; #define PG8_BAR __builtin_amdgcn_s_barrier()
; #define PG8_SCHED __builtin_amdgcn_sched_barrier(0)
; template <class Epi, class Sched, bool ALIGN_EPI = false, bool SP2 = false, bool ABLK = false, bool BBLK = false>
; __device__ __forceinline__ void gemm_phase(PG8_LAS unsigned char* lds, const Gemm g, const Sched& S, const Epi& E) {
;     ...
;             PG8_LDA(At, 1, 1); PG8_STAGE(PG8_SB(1, 0), b3, voffB); PG8_STAGE(PG8_SB(1, 1), b3 + hstepB, voffB); PG8_STAGE(PG8_SA(1, 0), a3, voffA);
;             PG8_WAIT_V(8); PG8_WAIT_L(0); PG8_BAR; PG8_MMA(1, 0, At, B0); PG8_MMA(1, 1, At, B1); PG8_BAR; PG8_SCHED;
;     ...
;         if constexpr (ALIGN_EPI) { if (wr == 0) PG8_BAR; }
	s_add_u32 s26, s24, 0x8000
	s_addc_u32 s27, s25, 0
	s_add_i32 s13, s13, s31
	s_mov_b32 m0, s13
	ds_read_b128 v[186:189], v161 offset:49152
	ds_read_b128 v[190:193], v161 offset:50176
	ds_read_b128 v[194:197], v161 offset:51200
	ds_read_b128 v[198:201], v161 offset:52224
	ds_read_b128 v[202:205], v161 offset:53248
	ds_read_b128 v[206:209], v161 offset:54272
	ds_read_b128 v[210:213], v161 offset:55296
	ds_read_b128 v[214:217], v161 offset:56320
	global_load_lds_dwordx4 v140, s[26:27]
	s_add_i32 m0, s13, 0x2000
	s_add_u32 s24, s24, 0xc000
	s_addc_u32 s25, s25, 0
	s_add_i32 s13, s68, s31
	global_load_lds_dwordx4 v136, s[26:27]
	s_mov_b32 m0, s13
	s_nop 0
	global_load_lds_dwordx4 v140, s[24:25]
	s_add_i32 m0, s13, 0x2000
	s_nop 0
	global_load_lds_dwordx4 v136, s[24:25]
	s_mov_b32 m0, s62
	s_nop 0
	global_load_lds_dwordx4 v142, s[22:23]
	s_mov_b32 m0, s63
	s_nop 0
	global_load_lds_dwordx4 v138, s[22:23]
	s_waitcnt vmcnt(8)
	s_waitcnt lgkmcnt(0)
	v_mfma_f32_16x16x32_bf16 v[68:71], v[152:155], v[186:189], v[68:71]
	v_mfma_f32_16x16x32_bf16 v[68:71], v[156:159], v[190:193], v[68:71]
	v_mfma_f32_16x16x32_bf16 v[64:67], v[166:169], v[190:193], v[64:67]
	v_mfma_f32_16x16x32_bf16 v[64:67], v[162:165], v[186:189], v[64:67]
	s_barrier
	s_setprio 1
	v_mfma_f32_16x16x32_bf16 v[60:63], v[170:173], v[186:189], v[60:63]
	v_mfma_f32_16x16x32_bf16 v[60:63], v[174:177], v[190:193], v[60:63]
	v_mfma_f32_16x16x32_bf16 v[56:59], v[182:185], v[190:193], v[56:59]
	v_mfma_f32_16x16x32_bf16 v[56:59], v[178:181], v[186:189], v[56:59]
	v_mfma_f32_16x16x32_bf16 v[40:43], v[178:181], v[194:197], v[40:43]
	v_mfma_f32_16x16x32_bf16 v[40:43], v[182:185], v[198:201], v[40:43]
	v_mfma_f32_16x16x32_bf16 v[52:55], v[156:159], v[198:201], v[52:55]
	v_mfma_f32_16x16x32_bf16 v[52:55], v[152:155], v[194:197], v[52:55]
	v_mfma_f32_16x16x32_bf16 v[48:51], v[162:165], v[194:197], v[48:51]
	v_mfma_f32_16x16x32_bf16 v[48:51], v[166:169], v[198:201], v[48:51]
	v_mfma_f32_16x16x32_bf16 v[44:47], v[174:177], v[198:201], v[44:47]
	v_mfma_f32_16x16x32_bf16 v[44:47], v[170:173], v[194:197], v[44:47]
	s_setprio 0
	s_setprio 1
	v_mfma_f32_16x16x32_bf16 v[24:27], v[170:173], v[202:205], v[24:27]
	v_mfma_f32_16x16x32_bf16 v[24:27], v[174:177], v[206:209], v[24:27]
	v_mfma_f32_16x16x32_bf16 v[32:35], v[156:159], v[206:209], v[32:35]
	v_mfma_f32_16x16x32_bf16 v[32:35], v[152:155], v[202:205], v[32:35]
	v_mfma_f32_16x16x32_bf16 v[28:31], v[162:165], v[202:205], v[28:31]
	v_mfma_f32_16x16x32_bf16 v[28:31], v[166:169], v[206:209], v[28:31]
	v_mfma_f32_16x16x32_bf16 v[20:23], v[182:185], v[206:209], v[20:23]
	v_mfma_f32_16x16x32_bf16 v[20:23], v[178:181], v[202:205], v[20:23]
	v_mfma_f32_16x16x32_bf16 v[4:7], v[178:181], v[210:213], v[4:7]
	v_mfma_f32_16x16x32_bf16 v[4:7], v[182:185], v[214:217], v[4:7]
	v_mfma_f32_16x16x32_bf16 v[16:19], v[156:159], v[214:217], v[16:19]
	v_mfma_f32_16x16x32_bf16 v[16:19], v[152:155], v[210:213], v[16:19]
	v_mfma_f32_16x16x32_bf16 v[12:15], v[162:165], v[210:213], v[12:15]
	v_mfma_f32_16x16x32_bf16 v[12:15], v[166:169], v[214:217], v[12:15]
	v_mfma_f32_16x16x32_bf16 v[8:11], v[174:177], v[214:217], v[8:11]
	v_mfma_f32_16x16x32_bf16 v[8:11], v[170:173], v[210:213], v[8:11]
	s_setprio 0
	s_barrier
	s_add_i32 vcc_hi, vcc_hi, 2
	s_add_u32 s20, s20, 0x10000
	s_addc_u32 s21, s21, 0
	s_add_u32 s77, s77, 0x10000
	s_addc_u32 vcc_lo, vcc_lo, 0
	s_cmp_gt_u32 vcc_hi, 29
	s_cbranch_scc0 .LBB0_185
	s_and_b64 vcc, exec, s[4:5]
	s_cbranch_vccz .LBB0_188
	s_barrier

; #define PG8_STAGE(bufoff, gbase, voff) do { _Pragma("unroll") for (int _i = 0; _i < 2; ++_i) \
;         __builtin_amdgcn_global_load_lds((const unsigned*)((const char*)(gbase) + (voff)[_i]), (PG8_LAS unsigned*)(lds + (bufoff) + ldsw + _i * 8192), 16, 0, 0); } while (0)
; #define PG8_LDA(dst, b, h) do { _Pragma("unroll") for (int m = 0; m < 4; ++m) _Pragma("unroll") for (int k = 0; k < 2; ++k) dst[m][k] = *(const PG8_LAS bf16x8*)(lds + PG8_SA(b, h) + aoff + m * 2048 + k * 1024); } while (0)
; #define PG8_LDB(dst, b, h) do { _Pragma("unroll") for (int n = 0; n < 2; ++n) _Pragma("unroll") for (int k = 0; k < 2; ++k) dst[n][k] = *(const PG8_LAS bf16x8*)(lds + PG8_SB(b, h) + boff + n * 2048 + k * 1024); } while (0)
; #define PG8_MMA(ai, bj, At, Bt) do { __builtin_amdgcn_s_setprio(1); _Pragma("unroll") for (int m = 0; m < 4; ++m) _Pragma("unroll") for (int n = 0; n < 2; ++n) _Pragma("unroll") for (int k = 0; k < 2; ++k) \
;         acc[ai][bj][m][n] = __builtin_amdgcn_mfma_f32_16x16x32_bf16(Bt[n][k], At[m][k], acc[ai][bj][m][n], 0, 0, 0); __builtin_amdgcn_s_setprio(0); } while (0)
; #define PG8_WAIT_V(n) asm volatile("s_waitcnt vmcnt(" #n ")" ::: "memory")
; #define PG8_BAR __builtin_amdgcn_s_barrier()
; template <class Epi, class Sched, bool ALIGN_EPI = false, bool SP2 = false, bool ABLK = false, bool BBLK = false>
; __device__ __forceinline__ void gemm_phase(PG8_LAS unsigned char* lds, const Gemm g, const Sched& S, const Epi& E) {
;     ...
;             const bool last = (t == nt - 2);
;             const char* a1 = cA + (size_t)(t + 1) * kstepA;
;             const char* a2 = last ? nA : cA + (size_t)(t + 2) * kstepA; const char* b2 = last ? nB : cB + (size_t)(t + 2) * kstepB;
;             const char* a3 = a2 + kstepA; const char* b3 = b2 + kstepB;
;             if (last && has_next) S.a_ready(nxt);
;             if constexpr (SP2) {
;             PG8_LDB(B0, 0, 0); PG8_LDB(B1, 0, 1); PG8_SCHED; PG8_LDA(At, 0, 0); PG8_STAGE(PG8_SA(1, 1), a1 + hstepA, voffA);
;             PG8_WAIT_V(8); PG8_WAIT_L(0); PG8_BAR; PG8_MMA(0, 0, At, B0); PG8_MMA(0, 1, At, B1); PG8_BAR; PG8_SCHED;
;             PG8_LDA(At, 0, 1); PG8_STAGE(PG8_SB(0, 0), b2, voffB); PG8_STAGE(PG8_SB(0, 1), b2 + hstepB, voffB); PG8_STAGE(PG8_SA(0, 0), a2, voffA);
;             PG8_WAIT_V(8); PG8_WAIT_L(0); PG8_BAR; PG8_MMA(1, 0, At, B0); PG8_MMA(1, 1, At, B1); PG8_BAR; PG8_SCHED;
.LBB0_439:
	s_add_u32 s16, s10, 0x4000
	s_addc_u32 s17, s11, 0
	s_cmpk_eq_i32 s13, 0x54
	s_cselect_b32 s20, s0, s16
	s_cselect_b32 s21, s1, s17
	s_cselect_b32 s18, s8, vcc_lo
	s_cselect_b32 s19, s9, vcc_hi
	s_add_u32 s16, s20, 0x8000
	s_addc_u32 s17, s21, 0
	s_add_i32 s68, 0, 0x10000
	v_add_u32_e32 v36, s68, v148
	s_add_i32 s88, 0, 0x14000
	ds_read_b128 v[152:155], v36
	ds_read_b128 v[156:159], v36 offset:1024
	ds_read_b128 v[160:163], v36 offset:2048
	ds_read_b128 v[164:167], v36 offset:3072
	v_add_u32_e32 v36, s88, v148
	ds_read_b128 v[168:171], v36
	ds_read_b128 v[172:175], v36 offset:1024
	ds_read_b128 v[176:179], v36 offset:2048
	ds_read_b128 v[180:183], v36 offset:3072
	s_add_i32 m0, s27, 0xc000
	ds_read_b128 v[184:187], v150
	ds_read_b128 v[188:191], v150 offset:1024
	ds_read_b128 v[192:195], v150 offset:2048
	ds_read_b128 v[196:199], v150 offset:3072
	ds_read_b128 v[200:203], v150 offset:4096
	ds_read_b128 v[204:207], v150 offset:5120
	ds_read_b128 v[208:211], v150 offset:6144
	ds_read_b128 v[212:215], v150 offset:7168
	global_load_lds_dwordx4 v144, s[10:11]
	s_add_i32 m0, s27, 0xe000
	s_nop 0
	global_load_lds_dwordx4 v146, s[10:11]
	s_waitcnt vmcnt(8)
	s_waitcnt lgkmcnt(0)
	v_mfma_f32_16x16x32_bf16 v[132:135], v[152:155], v[184:187], v[132:135]
	v_mfma_f32_16x16x32_bf16 v[132:135], v[156:159], v[188:191], v[132:135]
	v_mfma_f32_16x16x32_bf16 v[128:131], v[164:167], v[188:191], v[128:131]
	v_mfma_f32_16x16x32_bf16 v[128:131], v[160:163], v[184:187], v[128:131]
	s_barrier
	s_setprio 1
	v_mfma_f32_16x16x32_bf16 v[116:119], v[168:171], v[184:187], v[116:119]
	v_mfma_f32_16x16x32_bf16 v[116:119], v[172:175], v[188:191], v[116:119]
	v_mfma_f32_16x16x32_bf16 v[112:115], v[180:183], v[188:191], v[112:115]
	v_mfma_f32_16x16x32_bf16 v[112:115], v[176:179], v[184:187], v[112:115]
	v_mfma_f32_16x16x32_bf16 v[96:99], v[176:179], v[192:195], v[96:99]
	v_mfma_f32_16x16x32_bf16 v[96:99], v[180:183], v[196:199], v[96:99]
	v_mfma_f32_16x16x32_bf16 v[124:127], v[156:159], v[196:199], v[124:127]
	v_mfma_f32_16x16x32_bf16 v[124:127], v[152:155], v[192:195], v[124:127]
	v_mfma_f32_16x16x32_bf16 v[120:123], v[160:163], v[192:195], v[120:123]
	v_mfma_f32_16x16x32_bf16 v[120:123], v[164:167], v[196:199], v[120:123]
	v_mfma_f32_16x16x32_bf16 v[100:103], v[172:175], v[196:199], v[100:103]
	v_mfma_f32_16x16x32_bf16 v[100:103], v[168:171], v[192:195], v[100:103]
	s_setprio 0
	s_setprio 1
	v_mfma_f32_16x16x32_bf16 v[84:87], v[168:171], v[200:203], v[84:87]
	v_mfma_f32_16x16x32_bf16 v[84:87], v[172:175], v[204:207], v[84:87]
	v_mfma_f32_16x16x32_bf16 v[108:111], v[156:159], v[204:207], v[108:111]
	v_mfma_f32_16x16x32_bf16 v[108:111], v[152:155], v[200:203], v[108:111]
	v_mfma_f32_16x16x32_bf16 v[104:107], v[160:163], v[200:203], v[104:107]
	v_mfma_f32_16x16x32_bf16 v[104:107], v[164:167], v[204:207], v[104:107]
	v_mfma_f32_16x16x32_bf16 v[80:83], v[180:183], v[204:207], v[80:83]
	v_mfma_f32_16x16x32_bf16 v[80:83], v[176:179], v[200:203], v[80:83]
	v_mfma_f32_16x16x32_bf16 v[72:75], v[176:179], v[208:211], v[72:75]
	v_mfma_f32_16x16x32_bf16 v[72:75], v[180:183], v[212:215], v[72:75]
	v_mfma_f32_16x16x32_bf16 v[92:95], v[156:159], v[212:215], v[92:95]
	v_mfma_f32_16x16x32_bf16 v[92:95], v[152:155], v[208:211], v[92:95]
	v_mfma_f32_16x16x32_bf16 v[88:91], v[160:163], v[208:211], v[88:91]
	v_mfma_f32_16x16x32_bf16 v[88:91], v[164:167], v[212:215], v[88:91]
	v_mfma_f32_16x16x32_bf16 v[76:79], v[172:175], v[212:215], v[76:79]
	v_mfma_f32_16x16x32_bf16 v[76:79], v[168:171], v[208:211], v[76:79]
	s_setprio 0
	s_barrier
	s_add_i32 s68, s68, s24
	s_mov_b32 m0, s68
	ds_read_b128 v[184:187], v150 offset:16384
	ds_read_b128 v[188:191], v150 offset:17408
	ds_read_b128 v[192:195], v150 offset:18432
	ds_read_b128 v[196:199], v150 offset:19456
	ds_read_b128 v[200:203], v150 offset:20480
	ds_read_b128 v[204:207], v150 offset:21504
	ds_read_b128 v[208:211], v150 offset:22528
	ds_read_b128 v[212:215], v150 offset:23552
	global_load_lds_dwordx4 v138, s[18:19]
	s_add_i32 m0, s68, 0x2000
	s_add_u32 s68, s18, 0x4000
	s_addc_u32 s69, s19, 0
	s_add_i32 s88, s88, s24
	global_load_lds_dwordx4 v142, s[18:19]
	s_mov_b32 m0, s88
	s_nop 0
	global_load_lds_dwordx4 v138, s[68:69]
	s_add_i32 m0, s88, 0x2000
	s_nop 0
	global_load_lds_dwordx4 v142, s[68:69]
	s_mov_b32 m0, s27
	s_nop 0
	global_load_lds_dwordx4 v136, s[20:21]
	s_mov_b32 m0, s28
	s_nop 0
	global_load_lds_dwordx4 v140, s[20:21]
	s_waitcnt vmcnt(8)
	s_waitcnt lgkmcnt(0)
	v_mfma_f32_16x16x32_bf16 v[68:71], v[152:155], v[184:187], v[68:71]
	v_mfma_f32_16x16x32_bf16 v[68:71], v[156:159], v[188:191], v[68:71]
	v_mfma_f32_16x16x32_bf16 v[64:67], v[164:167], v[188:191], v[64:67]
	v_mfma_f32_16x16x32_bf16 v[64:67], v[160:163], v[184:187], v[64:67]
	s_barrier
; #define PG8_STAGE(bufoff, gbase, voff) do { _Pragma("unroll") for (int _i = 0; _i < 2; ++_i) \
;         __builtin_amdgcn_global_load_lds((const unsigned*)((const char*)(gbase) + (voff)[_i]), (PG8_LAS unsigned*)(lds + (bufoff) + ldsw + _i * 8192), 16, 0, 0); } while (0)
; #define PG8_LDA(dst, b, h) do { _Pragma("unroll") for (int m = 0; m < 4; ++m) _Pragma("unroll") for (int k = 0; k < 2; ++k) dst[m][k] = *(const PG8_LAS bf16x8*)(lds + PG8_SA(b, h) + aoff + m * 2048 + k * 1024); } while (0)
; #define PG8_LDB(dst, b, h) do { _Pragma("unroll") for (int n = 0; n < 2; ++n) _Pragma("unroll") for (int k = 0; k < 2; ++k) dst[n][k] = *(const PG8_LAS bf16x8*)(lds + PG8_SB(b, h) + boff + n * 2048 + k * 1024); } while (0)
; #define PG8_MMA(ai, bj, At, Bt) do { __builtin_amdgcn_s_setprio(1); _Pragma("unroll") for (int m = 0; m < 4; ++m) _Pragma("unroll") for (int n = 0; n < 2; ++n) _Pragma("unroll") for (int k = 0; k < 2; ++k) \
;         acc[ai][bj][m][n] = __builtin_amdgcn_mfma_f32_16x16x32_bf16(Bt[n][k], At[m][k], acc[ai][bj][m][n], 0, 0, 0); __builtin_amdgcn_s_setprio(0); } while (0)
; #define PG8_WAIT_V(n) asm volatile("s_waitcnt vmcnt(" #n ")" ::: "memory")
; #define PG8_WAIT_L(n) asm volatile("s_waitcnt lgkmcnt(" #n ")" ::: "memory")
; #define PG8_BAR __builtin_amdgcn_s_barrier()
; #define PG8_SCHED __builtin_amdgcn_sched_barrier(0)
; template <class Epi, class Sched, bool ALIGN_EPI = false, bool SP2 = false, bool ABLK = false, bool BBLK = false>
; __device__ __forceinline__ void gemm_phase(PG8_LAS unsigned char* lds, const Gemm g, const Sched& S, const Epi& E) {
;     ...
;             PG8_WAIT_V(8); PG8_WAIT_L(0); PG8_BAR; PG8_MMA(1, 0, At, B0); PG8_MMA(1, 1, At, B1); PG8_BAR; PG8_SCHED;
;             PG8_LDB(B0, 1, 0); PG8_LDB(B1, 1, 1); PG8_SCHED; PG8_LDA(At, 1, 0); PG8_STAGE(PG8_SA(0, 1), a2 + hstepA, voffA);
;             PG8_WAIT_V(8); PG8_WAIT_L(0); PG8_BAR; PG8_MMA(0, 0, At, B0); PG8_MMA(0, 1, At, B1); PG8_BAR; PG8_SCHED;
	s_setprio 1
	v_mfma_f32_16x16x32_bf16 v[52:55], v[168:171], v[184:187], v[52:55]
	v_mfma_f32_16x16x32_bf16 v[52:55], v[172:175], v[188:191], v[52:55]
	v_mfma_f32_16x16x32_bf16 v[48:51], v[180:183], v[188:191], v[48:51]
	v_mfma_f32_16x16x32_bf16 v[48:51], v[176:179], v[184:187], v[48:51]
	v_mfma_f32_16x16x32_bf16 v[28:31], v[176:179], v[192:195], v[28:31]
	v_mfma_f32_16x16x32_bf16 v[28:31], v[180:183], v[196:199], v[28:31]
	v_mfma_f32_16x16x32_bf16 v[60:63], v[156:159], v[196:199], v[60:63]
	v_mfma_f32_16x16x32_bf16 v[60:63], v[152:155], v[192:195], v[60:63]
	v_mfma_f32_16x16x32_bf16 v[56:59], v[160:163], v[192:195], v[56:59]
	v_mfma_f32_16x16x32_bf16 v[56:59], v[164:167], v[196:199], v[56:59]
	v_mfma_f32_16x16x32_bf16 v[32:35], v[172:175], v[196:199], v[32:35]
	v_mfma_f32_16x16x32_bf16 v[32:35], v[168:171], v[192:195], v[32:35]
	s_setprio 0
	s_setprio 1
	v_mfma_f32_16x16x32_bf16 v[16:19], v[168:171], v[200:203], v[16:19]
	v_mfma_f32_16x16x32_bf16 v[16:19], v[172:175], v[204:207], v[16:19]
	v_mfma_f32_16x16x32_bf16 v[44:47], v[156:159], v[204:207], v[44:47]
	v_mfma_f32_16x16x32_bf16 v[44:47], v[152:155], v[200:203], v[44:47]
	v_mfma_f32_16x16x32_bf16 v[40:43], v[160:163], v[200:203], v[40:43]
	v_mfma_f32_16x16x32_bf16 v[40:43], v[164:167], v[204:207], v[40:43]
	v_mfma_f32_16x16x32_bf16 v[12:15], v[180:183], v[204:207], v[12:15]
	v_mfma_f32_16x16x32_bf16 v[12:15], v[176:179], v[200:203], v[12:15]
	v_mfma_f32_16x16x32_bf16 v[4:7], v[176:179], v[208:211], v[4:7]
	v_mfma_f32_16x16x32_bf16 v[4:7], v[180:183], v[212:215], v[4:7]
	v_mfma_f32_16x16x32_bf16 v[24:27], v[156:159], v[212:215], v[24:27]
	v_mfma_f32_16x16x32_bf16 v[24:27], v[152:155], v[208:211], v[24:27]
	v_mfma_f32_16x16x32_bf16 v[20:23], v[160:163], v[208:211], v[20:23]
	v_mfma_f32_16x16x32_bf16 v[20:23], v[164:167], v[212:215], v[20:23]
	v_mfma_f32_16x16x32_bf16 v[8:11], v[172:175], v[212:215], v[8:11]
	v_mfma_f32_16x16x32_bf16 v[8:11], v[168:171], v[208:211], v[8:11]
	s_setprio 0
	s_barrier
	s_add_i32 s68, 0, 0x18000
	v_add_u32_e32 v36, s68, v148
	s_add_i32 s69, 0, 0x1c000
	ds_read_b128 v[152:155], v36
	ds_read_b128 v[156:159], v36 offset:1024
	ds_read_b128 v[160:163], v36 offset:2048
	ds_read_b128 v[164:167], v36 offset:3072
	v_add_u32_e32 v36, s69, v148
	ds_read_b128 v[168:171], v36
	ds_read_b128 v[172:175], v36 offset:1024
	ds_read_b128 v[176:179], v36 offset:2048
	ds_read_b128 v[180:183], v36 offset:3072
	s_add_u32 s20, s20, 0x4000
	s_addc_u32 s21, s21, 0
	s_mov_b32 m0, s29
	ds_read_b128 v[184:187], v150 offset:32768
	ds_read_b128 v[188:191], v150 offset:33792
	ds_read_b128 v[192:195], v150 offset:34816
	ds_read_b128 v[196:199], v150 offset:35840
	ds_read_b128 v[200:203], v150 offset:36864
	ds_read_b128 v[204:207], v150 offset:37888
	ds_read_b128 v[208:211], v150 offset:38912
	ds_read_b128 v[212:215], v150 offset:39936
	global_load_lds_dwordx4 v136, s[20:21]
	s_mov_b32 m0, s30
	s_nop 0
	global_load_lds_dwordx4 v140, s[20:21]
	s_waitcnt vmcnt(8)
	s_waitcnt lgkmcnt(0)
	v_mfma_f32_16x16x32_bf16 v[132:135], v[152:155], v[184:187], v[132:135]
	v_mfma_f32_16x16x32_bf16 v[132:135], v[156:159], v[188:191], v[132:135]
	v_mfma_f32_16x16x32_bf16 v[128:131], v[164:167], v[188:191], v[128:131]
	v_mfma_f32_16x16x32_bf16 v[128:131], v[160:163], v[184:187], v[128:131]
	s_barrier
	s_setprio 1
	v_mfma_f32_16x16x32_bf16 v[116:119], v[168:171], v[184:187], v[116:119]
	v_mfma_f32_16x16x32_bf16 v[116:119], v[172:175], v[188:191], v[116:119]
	v_mfma_f32_16x16x32_bf16 v[112:115], v[180:183], v[188:191], v[112:115]
	v_mfma_f32_16x16x32_bf16 v[112:115], v[176:179], v[184:187], v[112:115]
	v_mfma_f32_16x16x32_bf16 v[96:99], v[176:179], v[192:195], v[96:99]
	v_mfma_f32_16x16x32_bf16 v[96:99], v[180:183], v[196:199], v[96:99]
	v_mfma_f32_16x16x32_bf16 v[124:127], v[156:159], v[196:199], v[124:127]
	v_mfma_f32_16x16x32_bf16 v[124:127], v[152:155], v[192:195], v[124:127]
	v_mfma_f32_16x16x32_bf16 v[120:123], v[160:163], v[192:195], v[120:123]
	v_mfma_f32_16x16x32_bf16 v[120:123], v[164:167], v[196:199], v[120:123]
	v_mfma_f32_16x16x32_bf16 v[100:103], v[172:175], v[196:199], v[100:103]
	v_mfma_f32_16x16x32_bf16 v[100:103], v[168:171], v[192:195], v[100:103]
	s_setprio 0
	s_setprio 1
	v_mfma_f32_16x16x32_bf16 v[84:87], v[168:171], v[200:203], v[84:87]
	v_mfma_f32_16x16x32_bf16 v[84:87], v[172:175], v[204:207], v[84:87]
	v_mfma_f32_16x16x32_bf16 v[108:111], v[156:159], v[204:207], v[108:111]
	v_mfma_f32_16x16x32_bf16 v[108:111], v[152:155], v[200:203], v[108:111]
	v_mfma_f32_16x16x32_bf16 v[104:107], v[160:163], v[200:203], v[104:107]
	v_mfma_f32_16x16x32_bf16 v[104:107], v[164:167], v[204:207], v[104:107]
	v_mfma_f32_16x16x32_bf16 v[80:83], v[180:183], v[204:207], v[80:83]
	v_mfma_f32_16x16x32_bf16 v[80:83], v[176:179], v[200:203], v[80:83]
	v_mfma_f32_16x16x32_bf16 v[72:75], v[176:179], v[208:211], v[72:75]
	v_mfma_f32_16x16x32_bf16 v[72:75], v[180:183], v[212:215], v[72:75]
	v_mfma_f32_16x16x32_bf16 v[92:95], v[156:159], v[212:215], v[92:95]
	v_mfma_f32_16x16x32_bf16 v[92:95], v[152:155], v[208:211], v[92:95]
	v_mfma_f32_16x16x32_bf16 v[88:91], v[160:163], v[208:211], v[88:91]
	v_mfma_f32_16x16x32_bf16 v[88:91], v[164:167], v[212:215], v[88:91]
	v_mfma_f32_16x16x32_bf16 v[76:79], v[172:175], v[212:215], v[76:79]
	v_mfma_f32_16x16x32_bf16 v[76:79], v[168:171], v[208:211], v[76:79]
	s_setprio 0
	s_barrier
; #define PG8_STAGE(bufoff, gbase, voff) do { _Pragma("unroll") for (int _i = 0; _i < 2; ++_i) \
;         __builtin_amdgcn_global_load_lds((const unsigned*)((const char*)(gbase) + (voff)[_i]), (PG8_LAS unsigned*)(lds + (bufoff) + ldsw + _i * 8192), 16, 0, 0); } while (0)
; #define PG8_LDA(dst, b, h) do { _Pragma("unroll") for (int m = 0; m < 4; ++m) _Pragma("unroll") for (int k = 0; k < 2; ++k) dst[m][k] = *(const PG8_LAS bf16x8*)(lds + PG8_SA(b, h) + aoff + m * 2048 + k * 1024); } while (0)
; #define PG8_MMA(ai, bj, At, Bt) do { __builtin_amdgcn_s_setprio(1); _Pragma("unroll") for (int m = 0; m < 4; ++m) _Pragma("unroll") for (int n = 0; n < 2; ++n) _Pragma("unroll") for (int k = 0; k < 2; ++k) \
;         acc[ai][bj][m][n] = __builtin_amdgcn_mfma_f32_16x16x32_bf16(Bt[n][k], At[m][k], acc[ai][bj][m][n], 0, 0, 0); __builtin_amdgcn_s_setprio(0); } while (0)
; #define PG8_WAIT_V(n) asm volatile("s_waitcnt vmcnt(" #n ")" ::: "memory")
; #define PG8_WAIT_L(n) asm volatile("s_waitcnt lgkmcnt(" #n ")" ::: "memory")
; #define PG8_BAR __builtin_amdgcn_s_barrier()
; #define PG8_SCHED __builtin_amdgcn_sched_barrier(0)
; template <class Epi, class Sched, bool ALIGN_EPI = false, bool SP2 = false, bool ABLK = false, bool BBLK = false>
; __device__ __forceinline__ void gemm_phase(PG8_LAS unsigned char* lds, const Gemm g, const Sched& S, const Epi& E) {
;     ...
;             PG8_LDA(At, 1, 1); PG8_STAGE(PG8_SB(1, 0), b3, voffB); PG8_STAGE(PG8_SB(1, 1), b3 + hstepB, voffB); PG8_STAGE(PG8_SA(1, 0), a3, voffA);
;             PG8_WAIT_V(8); PG8_WAIT_L(0); PG8_BAR; PG8_MMA(1, 0, At, B0); PG8_MMA(1, 1, At, B1); PG8_BAR; PG8_SCHED;
;     ...
;         if constexpr (ALIGN_EPI) { if (wr == 0) PG8_BAR; }
	s_add_u32 s20, s18, 0x8000
	s_addc_u32 s21, s19, 0
	s_add_i32 s68, s68, s24
	s_mov_b32 m0, s68
	ds_read_b128 v[184:187], v150 offset:49152
	ds_read_b128 v[188:191], v150 offset:50176
	ds_read_b128 v[192:195], v150 offset:51200
	ds_read_b128 v[196:199], v150 offset:52224
	ds_read_b128 v[200:203], v150 offset:53248
	ds_read_b128 v[204:207], v150 offset:54272
	ds_read_b128 v[208:211], v150 offset:55296
	ds_read_b128 v[212:215], v150 offset:56320
	global_load_lds_dwordx4 v138, s[20:21]
	s_add_i32 m0, s68, 0x2000
	s_add_u32 s18, s18, 0xc000
	s_addc_u32 s19, s19, 0
	global_load_lds_dwordx4 v142, s[20:21]
	s_add_i32 s20, s69, s24
	s_mov_b32 m0, s20
	s_nop 0
	global_load_lds_dwordx4 v138, s[18:19]
	s_add_i32 m0, s20, 0x2000
	s_nop 0
	global_load_lds_dwordx4 v142, s[18:19]
	s_mov_b32 m0, s35
	s_nop 0
	global_load_lds_dwordx4 v136, s[16:17]
	s_mov_b32 m0, s70
	s_nop 0
	global_load_lds_dwordx4 v140, s[16:17]
	s_waitcnt vmcnt(8)
	s_waitcnt lgkmcnt(0)
	v_mfma_f32_16x16x32_bf16 v[68:71], v[152:155], v[184:187], v[68:71]
	v_mfma_f32_16x16x32_bf16 v[68:71], v[156:159], v[188:191], v[68:71]
	v_mfma_f32_16x16x32_bf16 v[64:67], v[164:167], v[188:191], v[64:67]
	v_mfma_f32_16x16x32_bf16 v[64:67], v[160:163], v[184:187], v[64:67]
	s_barrier
	s_setprio 1
	v_mfma_f32_16x16x32_bf16 v[52:55], v[168:171], v[184:187], v[52:55]
	v_mfma_f32_16x16x32_bf16 v[52:55], v[172:175], v[188:191], v[52:55]
	v_mfma_f32_16x16x32_bf16 v[48:51], v[180:183], v[188:191], v[48:51]
	v_mfma_f32_16x16x32_bf16 v[48:51], v[176:179], v[184:187], v[48:51]
	v_mfma_f32_16x16x32_bf16 v[28:31], v[176:179], v[192:195], v[28:31]
	v_mfma_f32_16x16x32_bf16 v[28:31], v[180:183], v[196:199], v[28:31]
	v_mfma_f32_16x16x32_bf16 v[60:63], v[156:159], v[196:199], v[60:63]
	v_mfma_f32_16x16x32_bf16 v[60:63], v[152:155], v[192:195], v[60:63]
	v_mfma_f32_16x16x32_bf16 v[56:59], v[160:163], v[192:195], v[56:59]
	v_mfma_f32_16x16x32_bf16 v[56:59], v[164:167], v[196:199], v[56:59]
	v_mfma_f32_16x16x32_bf16 v[32:35], v[172:175], v[196:199], v[32:35]
	v_mfma_f32_16x16x32_bf16 v[32:35], v[168:171], v[192:195], v[32:35]
	s_setprio 0
	s_setprio 1
	v_mfma_f32_16x16x32_bf16 v[16:19], v[168:171], v[200:203], v[16:19]
	v_mfma_f32_16x16x32_bf16 v[16:19], v[172:175], v[204:207], v[16:19]
	v_mfma_f32_16x16x32_bf16 v[44:47], v[156:159], v[204:207], v[44:47]
	v_mfma_f32_16x16x32_bf16 v[44:47], v[152:155], v[200:203], v[44:47]
	v_mfma_f32_16x16x32_bf16 v[40:43], v[160:163], v[200:203], v[40:43]
	v_mfma_f32_16x16x32_bf16 v[40:43], v[164:167], v[204:207], v[40:43]
	v_mfma_f32_16x16x32_bf16 v[12:15], v[180:183], v[204:207], v[12:15]
	v_mfma_f32_16x16x32_bf16 v[12:15], v[176:179], v[200:203], v[12:15]
	v_mfma_f32_16x16x32_bf16 v[4:7], v[176:179], v[208:211], v[4:7]
	v_mfma_f32_16x16x32_bf16 v[4:7], v[180:183], v[212:215], v[4:7]
	v_mfma_f32_16x16x32_bf16 v[24:27], v[156:159], v[212:215], v[24:27]
	v_mfma_f32_16x16x32_bf16 v[24:27], v[152:155], v[208:211], v[24:27]
	v_mfma_f32_16x16x32_bf16 v[20:23], v[160:163], v[208:211], v[20:23]
	v_mfma_f32_16x16x32_bf16 v[20:23], v[164:167], v[212:215], v[20:23]
	v_mfma_f32_16x16x32_bf16 v[8:11], v[172:175], v[212:215], v[8:11]
	v_mfma_f32_16x16x32_bf16 v[8:11], v[168:171], v[208:211], v[8:11]
	s_setprio 0
	s_barrier
	s_add_i32 s13, s13, 2
	s_add_u32 s10, s10, 0x10000
	s_addc_u32 s11, s11, 0
	s_add_u32 vcc_lo, vcc_lo, 0x10000
	s_addc_u32 vcc_hi, vcc_hi, 0
	s_cmpk_gt_u32 s13, 0x55
	s_cbranch_scc0 .LBB0_439
	s_and_b64 vcc, exec, s[6:7]
	s_cbranch_vccz .LBB0_442
	s_barrier

; #define PG8_STAGE(bufoff, gbase, voff) do { _Pragma("unroll") for (int _i = 0; _i < 2; ++_i) \
;         __builtin_amdgcn_global_load_lds((const unsigned*)((const char*)(gbase) + (voff)[_i]), (PG8_LAS unsigned*)(lds + (bufoff) + ldsw + _i * 8192), 16, 0, 0); } while (0)
; #define PG8_LDA(dst, b, h) do { _Pragma("unroll") for (int m = 0; m < 4; ++m) _Pragma("unroll") for (int k = 0; k < 2; ++k) dst[m][k] = *(const PG8_LAS bf16x8*)(lds + PG8_SA(b, h) + aoff + m * 2048 + k * 1024); } while (0)
; #define PG8_LDB(dst, b, h) do { _Pragma("unroll") for (int n = 0; n < 2; ++n) _Pragma("unroll") for (int k = 0; k < 2; ++k) dst[n][k] = *(const PG8_LAS bf16x8*)(lds + PG8_SB(b, h) + boff + n * 2048 + k * 1024); } while (0)
; #define PG8_MMA(ai, bj, At, Bt) do { __builtin_amdgcn_s_setprio(1); _Pragma("unroll") for (int m = 0; m < 4; ++m) _Pragma("unroll") for (int n = 0; n < 2; ++n) _Pragma("unroll") for (int k = 0; k < 2; ++k) \
;         acc[ai][bj][m][n] = __builtin_amdgcn_mfma_f32_16x16x32_bf16(Bt[n][k], At[m][k], acc[ai][bj][m][n], 0, 0, 0); __builtin_amdgcn_s_setprio(0); } while (0)
; #define PG8_WAIT_V(n) asm volatile("s_waitcnt vmcnt(" #n ")" ::: "memory")
; #define PG8_BAR __builtin_amdgcn_s_barrier()
; template <class Epi, class Sched, bool ALIGN_EPI = false, bool SP2 = false, bool ABLK = false, bool BBLK = false>
; __device__ __forceinline__ void gemm_phase(PG8_LAS unsigned char* lds, const Gemm g, const Sched& S, const Epi& E) {
;     ...
;             const bool last = (t == nt - 2);
;             const char* a1 = cA + (size_t)(t + 1) * kstepA;
;             const char* a2 = last ? nA : cA + (size_t)(t + 2) * kstepA; const char* b2 = last ? nB : cB + (size_t)(t + 2) * kstepB;
;             const char* a3 = a2 + kstepA; const char* b3 = b2 + kstepB;
;             if (last && has_next) S.a_ready(nxt);
;             if constexpr (SP2) {
;             PG8_LDB(B0, 0, 0); PG8_LDB(B1, 0, 1); PG8_SCHED; PG8_LDA(At, 0, 0); PG8_STAGE(PG8_SA(1, 1), a1 + hstepA, voffA);
;             PG8_WAIT_V(8); PG8_WAIT_L(0); PG8_BAR; PG8_MMA(0, 0, At, B0); PG8_MMA(0, 1, At, B1); PG8_BAR; PG8_SCHED;
;             PG8_LDA(At, 0, 1); PG8_STAGE(PG8_SB(0, 0), b2, voffB); PG8_STAGE(PG8_SB(0, 1), b2 + hstepB, voffB); PG8_STAGE(PG8_SA(0, 0), a2, voffA);
;             PG8_WAIT_V(8); PG8_WAIT_L(0); PG8_BAR; PG8_MMA(1, 0, At, B0); PG8_MMA(1, 1, At, B1); PG8_BAR; PG8_SCHED;
.LBB0_916:
	s_add_u32 s22, s20, 0x4000
	s_addc_u32 s23, s21, 0
	s_cmp_eq_u32 s13, 28
	s_cselect_b32 s26, s19, s22
	s_cselect_b32 s27, s1, s23
	s_cselect_b32 s24, s65, s70
	s_cselect_b32 s25, s9, s71
	s_add_u32 s22, s26, 0x8000
	s_addc_u32 s23, s27, 0
	s_add_i32 s68, 0, 0x10000
	v_add_u32_e32 v36, s68, v155
	s_add_i32 s77, 0, 0x14000
	ds_read_b128 v[150:153], v36
	ds_read_b128 v[158:161], v36 offset:1024
	ds_read_b128 v[162:165], v36 offset:2048
	ds_read_b128 v[166:169], v36 offset:3072
	v_add_u32_e32 v36, s77, v155
	ds_read_b128 v[170:173], v36
	ds_read_b128 v[174:177], v36 offset:1024
	ds_read_b128 v[178:181], v36 offset:2048
	ds_read_b128 v[182:185], v36 offset:3072
	s_add_i32 m0, s31, 0xc000
	ds_read_b128 v[186:189], v157
	ds_read_b128 v[190:193], v157 offset:1024
	ds_read_b128 v[194:197], v157 offset:2048
	ds_read_b128 v[198:201], v157 offset:3072
	ds_read_b128 v[202:205], v157 offset:4096
	ds_read_b128 v[206:209], v157 offset:5120
	ds_read_b128 v[210:213], v157 offset:6144
	ds_read_b128 v[214:217], v157 offset:7168
	global_load_lds_dwordx4 v146, s[20:21]
	s_add_i32 m0, s31, 0xe000
	s_nop 0
	global_load_lds_dwordx4 v148, s[20:21]
	s_waitcnt vmcnt(8)
	s_waitcnt lgkmcnt(0)
	v_mfma_f32_16x16x32_bf16 v[132:135], v[150:153], v[186:189], v[132:135]
	v_mfma_f32_16x16x32_bf16 v[132:135], v[158:161], v[190:193], v[132:135]
	v_mfma_f32_16x16x32_bf16 v[128:131], v[166:169], v[190:193], v[128:131]
	v_mfma_f32_16x16x32_bf16 v[128:131], v[162:165], v[186:189], v[128:131]
	s_barrier
	s_setprio 1
	v_mfma_f32_16x16x32_bf16 v[120:123], v[170:173], v[186:189], v[120:123]
	v_mfma_f32_16x16x32_bf16 v[120:123], v[174:177], v[190:193], v[120:123]
	v_mfma_f32_16x16x32_bf16 v[112:115], v[182:185], v[190:193], v[112:115]
	v_mfma_f32_16x16x32_bf16 v[112:115], v[178:181], v[186:189], v[112:115]
	v_mfma_f32_16x16x32_bf16 v[96:99], v[178:181], v[194:197], v[96:99]
	v_mfma_f32_16x16x32_bf16 v[96:99], v[182:185], v[198:201], v[96:99]
	v_mfma_f32_16x16x32_bf16 v[124:127], v[158:161], v[198:201], v[124:127]
	v_mfma_f32_16x16x32_bf16 v[124:127], v[150:153], v[194:197], v[124:127]
	v_mfma_f32_16x16x32_bf16 v[116:119], v[162:165], v[194:197], v[116:119]
	v_mfma_f32_16x16x32_bf16 v[116:119], v[166:169], v[198:201], v[116:119]
	v_mfma_f32_16x16x32_bf16 v[104:107], v[174:177], v[198:201], v[104:107]
	v_mfma_f32_16x16x32_bf16 v[104:107], v[170:173], v[194:197], v[104:107]
	s_setprio 0
	s_setprio 1
	v_mfma_f32_16x16x32_bf16 v[88:91], v[170:173], v[202:205], v[88:91]
	v_mfma_f32_16x16x32_bf16 v[88:91], v[174:177], v[206:209], v[88:91]
	v_mfma_f32_16x16x32_bf16 v[108:111], v[158:161], v[206:209], v[108:111]
	v_mfma_f32_16x16x32_bf16 v[108:111], v[150:153], v[202:205], v[108:111]
	v_mfma_f32_16x16x32_bf16 v[100:103], v[162:165], v[202:205], v[100:103]
	v_mfma_f32_16x16x32_bf16 v[100:103], v[166:169], v[206:209], v[100:103]
	v_mfma_f32_16x16x32_bf16 v[80:83], v[182:185], v[206:209], v[80:83]
	v_mfma_f32_16x16x32_bf16 v[80:83], v[178:181], v[202:205], v[80:83]
	v_mfma_f32_16x16x32_bf16 v[72:75], v[178:181], v[210:213], v[72:75]
	v_mfma_f32_16x16x32_bf16 v[72:75], v[182:185], v[214:217], v[72:75]
	v_mfma_f32_16x16x32_bf16 v[92:95], v[158:161], v[214:217], v[92:95]
	v_mfma_f32_16x16x32_bf16 v[92:95], v[150:153], v[210:213], v[92:95]
	v_mfma_f32_16x16x32_bf16 v[84:87], v[162:165], v[210:213], v[84:87]
	v_mfma_f32_16x16x32_bf16 v[84:87], v[166:169], v[214:217], v[84:87]
	v_mfma_f32_16x16x32_bf16 v[76:79], v[174:177], v[214:217], v[76:79]
	v_mfma_f32_16x16x32_bf16 v[76:79], v[170:173], v[210:213], v[76:79]
	s_setprio 0
	s_barrier
	s_add_i32 s68, s68, s29
	s_mov_b32 m0, s68
	ds_read_b128 v[186:189], v157 offset:16384
	ds_read_b128 v[190:193], v157 offset:17408
	ds_read_b128 v[194:197], v157 offset:18432
	ds_read_b128 v[198:201], v157 offset:19456
	ds_read_b128 v[202:205], v157 offset:20480
	ds_read_b128 v[206:209], v157 offset:21504
	ds_read_b128 v[210:213], v157 offset:22528
	ds_read_b128 v[214:217], v157 offset:23552
	global_load_lds_dwordx4 v140, s[24:25]
	s_add_i32 m0, s68, 0x2000
	s_add_u32 s68, s24, 0x4000
	s_addc_u32 s69, s25, 0
	s_add_i32 s77, s77, s29
	global_load_lds_dwordx4 v136, s[24:25]
	s_mov_b32 m0, s77
	s_nop 0
	global_load_lds_dwordx4 v140, s[68:69]
	s_add_i32 m0, s77, 0x2000
	s_nop 0
	global_load_lds_dwordx4 v136, s[68:69]
	s_mov_b32 m0, s31
	s_nop 0
	global_load_lds_dwordx4 v142, s[26:27]
	s_mov_b32 m0, s34
	s_nop 0
	global_load_lds_dwordx4 v138, s[26:27]
	s_waitcnt vmcnt(8)
	s_waitcnt lgkmcnt(0)
	v_mfma_f32_16x16x32_bf16 v[68:71], v[150:153], v[186:189], v[68:71]
	v_mfma_f32_16x16x32_bf16 v[68:71], v[158:161], v[190:193], v[68:71]
	v_mfma_f32_16x16x32_bf16 v[64:67], v[166:169], v[190:193], v[64:67]
	v_mfma_f32_16x16x32_bf16 v[64:67], v[162:165], v[186:189], v[64:67]
	s_barrier
; #define PG8_STAGE(bufoff, gbase, voff) do { _Pragma("unroll") for (int _i = 0; _i < 2; ++_i) \
;         __builtin_amdgcn_global_load_lds((const unsigned*)((const char*)(gbase) + (voff)[_i]), (PG8_LAS unsigned*)(lds + (bufoff) + ldsw + _i * 8192), 16, 0, 0); } while (0)
; #define PG8_LDA(dst, b, h) do { _Pragma("unroll") for (int m = 0; m < 4; ++m) _Pragma("unroll") for (int k = 0; k < 2; ++k) dst[m][k] = *(const PG8_LAS bf16x8*)(lds + PG8_SA(b, h) + aoff + m * 2048 + k * 1024); } while (0)
; #define PG8_LDB(dst, b, h) do { _Pragma("unroll") for (int n = 0; n < 2; ++n) _Pragma("unroll") for (int k = 0; k < 2; ++k) dst[n][k] = *(const PG8_LAS bf16x8*)(lds + PG8_SB(b, h) + boff + n * 2048 + k * 1024); } while (0)
; #define PG8_MMA(ai, bj, At, Bt) do { __builtin_amdgcn_s_setprio(1); _Pragma("unroll") for (int m = 0; m < 4; ++m) _Pragma("unroll") for (int n = 0; n < 2; ++n) _Pragma("unroll") for (int k = 0; k < 2; ++k) \
;         acc[ai][bj][m][n] = __builtin_amdgcn_mfma_f32_16x16x32_bf16(Bt[n][k], At[m][k], acc[ai][bj][m][n], 0, 0, 0); __builtin_amdgcn_s_setprio(0); } while (0)
; #define PG8_WAIT_V(n) asm volatile("s_waitcnt vmcnt(" #n ")" ::: "memory")
; #define PG8_WAIT_L(n) asm volatile("s_waitcnt lgkmcnt(" #n ")" ::: "memory")
; #define PG8_BAR __builtin_amdgcn_s_barrier()
; #define PG8_SCHED __builtin_amdgcn_sched_barrier(0)
; template <class Epi, class Sched, bool ALIGN_EPI = false, bool SP2 = false, bool ABLK = false, bool BBLK = false>
; __device__ __forceinline__ void gemm_phase(PG8_LAS unsigned char* lds, const Gemm g, const Sched& S, const Epi& E) {
;     ...
;             PG8_WAIT_V(8); PG8_WAIT_L(0); PG8_BAR; PG8_MMA(1, 0, At, B0); PG8_MMA(1, 1, At, B1); PG8_BAR; PG8_SCHED;
;             PG8_LDB(B0, 1, 0); PG8_LDB(B1, 1, 1); PG8_SCHED; PG8_LDA(At, 1, 0); PG8_STAGE(PG8_SA(0, 1), a2 + hstepA, voffA);
;             PG8_WAIT_V(8); PG8_WAIT_L(0); PG8_BAR; PG8_MMA(0, 0, At, B0); PG8_MMA(0, 1, At, B1); PG8_BAR; PG8_SCHED;
	s_setprio 1
	v_mfma_f32_16x16x32_bf16 v[56:59], v[170:173], v[186:189], v[56:59]
	v_mfma_f32_16x16x32_bf16 v[56:59], v[174:177], v[190:193], v[56:59]
	v_mfma_f32_16x16x32_bf16 v[48:51], v[182:185], v[190:193], v[48:51]
	v_mfma_f32_16x16x32_bf16 v[48:51], v[178:181], v[186:189], v[48:51]
	v_mfma_f32_16x16x32_bf16 v[28:31], v[178:181], v[194:197], v[28:31]
	v_mfma_f32_16x16x32_bf16 v[28:31], v[182:185], v[198:201], v[28:31]
	v_mfma_f32_16x16x32_bf16 v[60:63], v[158:161], v[198:201], v[60:63]
	v_mfma_f32_16x16x32_bf16 v[60:63], v[150:153], v[194:197], v[60:63]
	v_mfma_f32_16x16x32_bf16 v[52:55], v[162:165], v[194:197], v[52:55]
	v_mfma_f32_16x16x32_bf16 v[52:55], v[166:169], v[198:201], v[52:55]
	v_mfma_f32_16x16x32_bf16 v[40:43], v[174:177], v[198:201], v[40:43]
	v_mfma_f32_16x16x32_bf16 v[40:43], v[170:173], v[194:197], v[40:43]
	s_setprio 0
	s_setprio 1
	v_mfma_f32_16x16x32_bf16 v[20:23], v[170:173], v[202:205], v[20:23]
	v_mfma_f32_16x16x32_bf16 v[20:23], v[174:177], v[206:209], v[20:23]
	v_mfma_f32_16x16x32_bf16 v[44:47], v[158:161], v[206:209], v[44:47]
	v_mfma_f32_16x16x32_bf16 v[44:47], v[150:153], v[202:205], v[44:47]
	v_mfma_f32_16x16x32_bf16 v[32:35], v[162:165], v[202:205], v[32:35]
	v_mfma_f32_16x16x32_bf16 v[32:35], v[166:169], v[206:209], v[32:35]
	v_mfma_f32_16x16x32_bf16 v[12:15], v[182:185], v[206:209], v[12:15]
	v_mfma_f32_16x16x32_bf16 v[12:15], v[178:181], v[202:205], v[12:15]
	v_mfma_f32_16x16x32_bf16 v[4:7], v[178:181], v[210:213], v[4:7]
	v_mfma_f32_16x16x32_bf16 v[4:7], v[182:185], v[214:217], v[4:7]
	v_mfma_f32_16x16x32_bf16 v[24:27], v[158:161], v[214:217], v[24:27]
	v_mfma_f32_16x16x32_bf16 v[24:27], v[150:153], v[210:213], v[24:27]
	v_mfma_f32_16x16x32_bf16 v[16:19], v[162:165], v[210:213], v[16:19]
	v_mfma_f32_16x16x32_bf16 v[16:19], v[166:169], v[214:217], v[16:19]
	v_mfma_f32_16x16x32_bf16 v[8:11], v[174:177], v[214:217], v[8:11]
	v_mfma_f32_16x16x32_bf16 v[8:11], v[170:173], v[210:213], v[8:11]
	s_setprio 0
	s_barrier
	s_add_i32 s68, 0, 0x18000
	v_add_u32_e32 v36, s68, v155
	s_add_i32 s69, 0, 0x1c000
	ds_read_b128 v[150:153], v36
	ds_read_b128 v[158:161], v36 offset:1024
	ds_read_b128 v[162:165], v36 offset:2048
	ds_read_b128 v[166:169], v36 offset:3072
	v_add_u32_e32 v36, s69, v155
	ds_read_b128 v[170:173], v36
	ds_read_b128 v[174:177], v36 offset:1024
	ds_read_b128 v[178:181], v36 offset:2048
	ds_read_b128 v[182:185], v36 offset:3072
	s_add_u32 s26, s26, 0x4000
	s_addc_u32 s27, s27, 0
	s_mov_b32 m0, s35
	ds_read_b128 v[186:189], v157 offset:32768
	ds_read_b128 v[190:193], v157 offset:33792
	ds_read_b128 v[194:197], v157 offset:34816
	ds_read_b128 v[198:201], v157 offset:35840
	ds_read_b128 v[202:205], v157 offset:36864
	ds_read_b128 v[206:209], v157 offset:37888
	ds_read_b128 v[210:213], v157 offset:38912
	ds_read_b128 v[214:217], v157 offset:39936
	global_load_lds_dwordx4 v142, s[26:27]
	s_mov_b32 m0, s36
	s_nop 0
	global_load_lds_dwordx4 v138, s[26:27]
	s_waitcnt vmcnt(8)
	s_waitcnt lgkmcnt(0)
	v_mfma_f32_16x16x32_bf16 v[132:135], v[150:153], v[186:189], v[132:135]
	v_mfma_f32_16x16x32_bf16 v[132:135], v[158:161], v[190:193], v[132:135]
	v_mfma_f32_16x16x32_bf16 v[128:131], v[166:169], v[190:193], v[128:131]
	v_mfma_f32_16x16x32_bf16 v[128:131], v[162:165], v[186:189], v[128:131]
	s_barrier
	s_setprio 1
	v_mfma_f32_16x16x32_bf16 v[120:123], v[170:173], v[186:189], v[120:123]
	v_mfma_f32_16x16x32_bf16 v[120:123], v[174:177], v[190:193], v[120:123]
	v_mfma_f32_16x16x32_bf16 v[112:115], v[182:185], v[190:193], v[112:115]
	v_mfma_f32_16x16x32_bf16 v[112:115], v[178:181], v[186:189], v[112:115]
	v_mfma_f32_16x16x32_bf16 v[96:99], v[178:181], v[194:197], v[96:99]
	v_mfma_f32_16x16x32_bf16 v[96:99], v[182:185], v[198:201], v[96:99]
	v_mfma_f32_16x16x32_bf16 v[124:127], v[158:161], v[198:201], v[124:127]
	v_mfma_f32_16x16x32_bf16 v[124:127], v[150:153], v[194:197], v[124:127]
	v_mfma_f32_16x16x32_bf16 v[116:119], v[162:165], v[194:197], v[116:119]
	v_mfma_f32_16x16x32_bf16 v[116:119], v[166:169], v[198:201], v[116:119]
	v_mfma_f32_16x16x32_bf16 v[104:107], v[174:177], v[198:201], v[104:107]
	v_mfma_f32_16x16x32_bf16 v[104:107], v[170:173], v[194:197], v[104:107]
	s_setprio 0
	s_setprio 1
	v_mfma_f32_16x16x32_bf16 v[88:91], v[170:173], v[202:205], v[88:91]
	v_mfma_f32_16x16x32_bf16 v[88:91], v[174:177], v[206:209], v[88:91]
	v_mfma_f32_16x16x32_bf16 v[108:111], v[158:161], v[206:209], v[108:111]
	v_mfma_f32_16x16x32_bf16 v[108:111], v[150:153], v[202:205], v[108:111]
	v_mfma_f32_16x16x32_bf16 v[100:103], v[162:165], v[202:205], v[100:103]
	v_mfma_f32_16x16x32_bf16 v[100:103], v[166:169], v[206:209], v[100:103]
	v_mfma_f32_16x16x32_bf16 v[80:83], v[182:185], v[206:209], v[80:83]
	v_mfma_f32_16x16x32_bf16 v[80:83], v[178:181], v[202:205], v[80:83]
	v_mfma_f32_16x16x32_bf16 v[72:75], v[178:181], v[210:213], v[72:75]
	v_mfma_f32_16x16x32_bf16 v[72:75], v[182:185], v[214:217], v[72:75]
	v_mfma_f32_16x16x32_bf16 v[92:95], v[158:161], v[214:217], v[92:95]
	v_mfma_f32_16x16x32_bf16 v[92:95], v[150:153], v[210:213], v[92:95]
	v_mfma_f32_16x16x32_bf16 v[84:87], v[162:165], v[210:213], v[84:87]
	v_mfma_f32_16x16x32_bf16 v[84:87], v[166:169], v[214:217], v[84:87]
	v_mfma_f32_16x16x32_bf16 v[76:79], v[174:177], v[214:217], v[76:79]
	v_mfma_f32_16x16x32_bf16 v[76:79], v[170:173], v[210:213], v[76:79]
	s_setprio 0
	s_barrier
; #define PG8_STAGE(bufoff, gbase, voff) do { _Pragma("unroll") for (int _i = 0; _i < 2; ++_i) \
;         __builtin_amdgcn_global_load_lds((const unsigned*)((const char*)(gbase) + (voff)[_i]), (PG8_LAS unsigned*)(lds + (bufoff) + ldsw + _i * 8192), 16, 0, 0); } while (0)
; #define PG8_LDA(dst, b, h) do { _Pragma("unroll") for (int m = 0; m < 4; ++m) _Pragma("unroll") for (int k = 0; k < 2; ++k) dst[m][k] = *(const PG8_LAS bf16x8*)(lds + PG8_SA(b, h) + aoff + m * 2048 + k * 1024); } while (0)
; #define PG8_MMA(ai, bj, At, Bt) do { __builtin_amdgcn_s_setprio(1); _Pragma("unroll") for (int m = 0; m < 4; ++m) _Pragma("unroll") for (int n = 0; n < 2; ++n) _Pragma("unroll") for (int k = 0; k < 2; ++k) \
;         acc[ai][bj][m][n] = __builtin_amdgcn_mfma_f32_16x16x32_bf16(Bt[n][k], At[m][k], acc[ai][bj][m][n], 0, 0, 0); __builtin_amdgcn_s_setprio(0); } while (0)
; #define PG8_WAIT_V(n) asm volatile("s_waitcnt vmcnt(" #n ")" ::: "memory")
; #define PG8_WAIT_L(n) asm volatile("s_waitcnt lgkmcnt(" #n ")" ::: "memory")
; #define PG8_BAR __builtin_amdgcn_s_barrier()
; #define PG8_SCHED __builtin_amdgcn_sched_barrier(0)
; template <class Epi, class Sched, bool ALIGN_EPI = false, bool SP2 = false, bool ABLK = false, bool BBLK = false>
; __device__ __forceinline__ void gemm_phase(PG8_LAS unsigned char* lds, const Gemm g, const Sched& S, const Epi& E) {
;     ...
;         for (int t = 0; t < nt; t += 2) {
;             const bool last = (t == nt - 2);
;     ...
;             PG8_LDA(At, 1, 1); PG8_STAGE(PG8_SB(1, 0), b3, voffB); PG8_STAGE(PG8_SB(1, 1), b3 + hstepB, voffB); PG8_STAGE(PG8_SA(1, 0), a3, voffA);
;             PG8_WAIT_V(8); PG8_WAIT_L(0); PG8_BAR; PG8_MMA(1, 0, At, B0); PG8_MMA(1, 1, At, B1); PG8_BAR; PG8_SCHED;
	s_add_u32 s26, s24, 0x8000
	s_addc_u32 s27, s25, 0
	s_add_i32 s68, s68, s29
	s_mov_b32 m0, s68
	ds_read_b128 v[186:189], v157 offset:49152
	ds_read_b128 v[190:193], v157 offset:50176
	ds_read_b128 v[194:197], v157 offset:51200
	ds_read_b128 v[198:201], v157 offset:52224
	ds_read_b128 v[202:205], v157 offset:53248
	ds_read_b128 v[206:209], v157 offset:54272
	ds_read_b128 v[210:213], v157 offset:55296
	ds_read_b128 v[214:217], v157 offset:56320
	global_load_lds_dwordx4 v140, s[26:27]
	s_add_i32 m0, s68, 0x2000
	s_add_u32 s24, s24, 0xc000
	s_addc_u32 s25, s25, 0
	global_load_lds_dwordx4 v136, s[26:27]
	s_add_i32 s26, s69, s29
	s_mov_b32 m0, s26
	s_nop 0
	global_load_lds_dwordx4 v140, s[24:25]
	s_add_i32 m0, s26, 0x2000
	s_nop 0
	global_load_lds_dwordx4 v136, s[24:25]
	s_mov_b32 m0, s37
	s_nop 0
	global_load_lds_dwordx4 v142, s[22:23]
	s_mov_b32 m0, s62
	s_nop 0
	global_load_lds_dwordx4 v138, s[22:23]
	s_waitcnt vmcnt(8)
	s_waitcnt lgkmcnt(0)
	v_mfma_f32_16x16x32_bf16 v[68:71], v[150:153], v[186:189], v[68:71]
	v_mfma_f32_16x16x32_bf16 v[68:71], v[158:161], v[190:193], v[68:71]
	v_mfma_f32_16x16x32_bf16 v[64:67], v[166:169], v[190:193], v[64:67]
	v_mfma_f32_16x16x32_bf16 v[64:67], v[162:165], v[186:189], v[64:67]
	s_barrier
	s_setprio 1
	v_mfma_f32_16x16x32_bf16 v[56:59], v[170:173], v[186:189], v[56:59]
	v_mfma_f32_16x16x32_bf16 v[56:59], v[174:177], v[190:193], v[56:59]
	v_mfma_f32_16x16x32_bf16 v[48:51], v[182:185], v[190:193], v[48:51]
	v_mfma_f32_16x16x32_bf16 v[48:51], v[178:181], v[186:189], v[48:51]
	v_mfma_f32_16x16x32_bf16 v[28:31], v[178:181], v[194:197], v[28:31]
	v_mfma_f32_16x16x32_bf16 v[28:31], v[182:185], v[198:201], v[28:31]
	v_mfma_f32_16x16x32_bf16 v[60:63], v[158:161], v[198:201], v[60:63]
	v_mfma_f32_16x16x32_bf16 v[60:63], v[150:153], v[194:197], v[60:63]
	v_mfma_f32_16x16x32_bf16 v[52:55], v[162:165], v[194:197], v[52:55]
	v_mfma_f32_16x16x32_bf16 v[52:55], v[166:169], v[198:201], v[52:55]
	v_mfma_f32_16x16x32_bf16 v[40:43], v[174:177], v[198:201], v[40:43]
	v_mfma_f32_16x16x32_bf16 v[40:43], v[170:173], v[194:197], v[40:43]
	s_setprio 0
	s_setprio 1
	v_mfma_f32_16x16x32_bf16 v[20:23], v[170:173], v[202:205], v[20:23]
	v_mfma_f32_16x16x32_bf16 v[20:23], v[174:177], v[206:209], v[20:23]
	v_mfma_f32_16x16x32_bf16 v[44:47], v[158:161], v[206:209], v[44:47]
	v_mfma_f32_16x16x32_bf16 v[44:47], v[150:153], v[202:205], v[44:47]
	v_mfma_f32_16x16x32_bf16 v[32:35], v[162:165], v[202:205], v[32:35]
	v_mfma_f32_16x16x32_bf16 v[32:35], v[166:169], v[206:209], v[32:35]
	v_mfma_f32_16x16x32_bf16 v[12:15], v[182:185], v[206:209], v[12:15]
	v_mfma_f32_16x16x32_bf16 v[12:15], v[178:181], v[202:205], v[12:15]
	v_mfma_f32_16x16x32_bf16 v[4:7], v[178:181], v[210:213], v[4:7]
	v_mfma_f32_16x16x32_bf16 v[4:7], v[182:185], v[214:217], v[4:7]
	v_mfma_f32_16x16x32_bf16 v[24:27], v[158:161], v[214:217], v[24:27]
	v_mfma_f32_16x16x32_bf16 v[24:27], v[150:153], v[210:213], v[24:27]
	v_mfma_f32_16x16x32_bf16 v[16:19], v[162:165], v[210:213], v[16:19]
	v_mfma_f32_16x16x32_bf16 v[16:19], v[166:169], v[214:217], v[16:19]
	v_mfma_f32_16x16x32_bf16 v[8:11], v[174:177], v[214:217], v[8:11]
	v_mfma_f32_16x16x32_bf16 v[8:11], v[170:173], v[210:213], v[8:11]
	s_setprio 0
	s_barrier
	s_add_i32 s13, s13, 2
	s_add_u32 s20, s20, 0x10000
	s_addc_u32 s21, s21, 0
	s_add_u32 s70, s70, 0x10000
	s_addc_u32 s71, s71, 0
	s_cmp_gt_u32 s13, 29
	s_cbranch_scc0 .LBB0_916
	s_and_b64 vcc, exec, s[6:7]
	s_cbranch_vccz .LBB0_919
	s_barrier

; #define PG8_STAGE(bufoff, gbase, voff) do { _Pragma("unroll") for (int _i = 0; _i < 2; ++_i) \
;         __builtin_amdgcn_global_load_lds((const unsigned*)((const char*)(gbase) + (voff)[_i]), (PG8_LAS unsigned*)(lds + (bufoff) + ldsw + _i * 8192), 16, 0, 0); } while (0)
; #define PG8_LDA(dst, b, h) do { _Pragma("unroll") for (int m = 0; m < 4; ++m) _Pragma("unroll") for (int k = 0; k < 2; ++k) dst[m][k] = *(const PG8_LAS bf16x8*)(lds + PG8_SA(b, h) + aoff + m * 2048 + k * 1024); } while (0)
; #define PG8_LDB(dst, b, h) do { _Pragma("unroll") for (int n = 0; n < 2; ++n) _Pragma("unroll") for (int k = 0; k < 2; ++k) dst[n][k] = *(const PG8_LAS bf16x8*)(lds + PG8_SB(b, h) + boff + n * 2048 + k * 1024); } while (0)
; #define PG8_MMA(ai, bj, At, Bt) do { __builtin_amdgcn_s_setprio(1); _Pragma("unroll") for (int m = 0; m < 4; ++m) _Pragma("unroll") for (int n = 0; n < 2; ++n) _Pragma("unroll") for (int k = 0; k < 2; ++k) \
;         acc[ai][bj][m][n] = __builtin_amdgcn_mfma_f32_16x16x32_bf16(Bt[n][k], At[m][k], acc[ai][bj][m][n], 0, 0, 0); __builtin_amdgcn_s_setprio(0); } while (0)
; #define PG8_WAIT_V(n) asm volatile("s_waitcnt vmcnt(" #n ")" ::: "memory")
; #define PG8_BAR __builtin_amdgcn_s_barrier()
; template <class Epi, class Sched, bool ALIGN_EPI = false, bool SP2 = false, bool ABLK = false, bool BBLK = false>
; __device__ __forceinline__ void gemm_phase(PG8_LAS unsigned char* lds, const Gemm g, const Sched& S, const Epi& E) {
;     ...
;             const bool last = (t == nt - 2);
;             const char* a1 = cA + (size_t)(t + 1) * kstepA;
;             const char* a2 = last ? nA : cA + (size_t)(t + 2) * kstepA; const char* b2 = last ? nB : cB + (size_t)(t + 2) * kstepB;
;             const char* a3 = a2 + kstepA; const char* b3 = b2 + kstepB;
;             if (last && has_next) S.a_ready(nxt);
;             if constexpr (SP2) {
;             PG8_LDB(B0, 0, 0); PG8_LDB(B1, 0, 1); PG8_SCHED; PG8_LDA(At, 0, 0); PG8_STAGE(PG8_SA(1, 1), a1 + hstepA, voffA);
;             PG8_WAIT_V(8); PG8_WAIT_L(0); PG8_BAR; PG8_MMA(0, 0, At, B0); PG8_MMA(0, 1, At, B1); PG8_BAR; PG8_SCHED;
;             PG8_LDA(At, 0, 1); PG8_STAGE(PG8_SB(0, 0), b2, voffB); PG8_STAGE(PG8_SB(0, 1), b2 + hstepB, voffB); PG8_STAGE(PG8_SA(0, 0), a2, voffA);
;             PG8_WAIT_V(8); PG8_WAIT_L(0); PG8_BAR; PG8_MMA(1, 0, At, B0); PG8_MMA(1, 1, At, B1); PG8_BAR; PG8_SCHED;
.LBB0_2111:
	s_add_u32 s24, s22, 0x4000
	s_addc_u32 s25, s23, 0
	s_cmp_eq_u32 s13, 28
	s_cselect_b32 s28, s17, s24
	s_cselect_b32 s29, s12, s25
	s_cselect_b32 s26, s77, s82
	s_cselect_b32 s27, s11, vcc_lo
	s_add_u32 s24, s28, 0x8000
	s_addc_u32 s25, s29, 0
	s_add_i32 s68, 0, 0x10000
	v_add_u32_e32 v151, s68, v148
	s_add_i32 s88, 0, 0x14000
	ds_read_b128 v[36:39], v151
	ds_read_b128 v[152:155], v151 offset:1024
	ds_read_b128 v[156:159], v151 offset:2048
	ds_read_b128 v[160:163], v151 offset:3072
	v_add_u32_e32 v151, s88, v148
	ds_read_b128 v[164:167], v151
	ds_read_b128 v[168:171], v151 offset:1024
	ds_read_b128 v[172:175], v151 offset:2048
	ds_read_b128 v[176:179], v151 offset:3072
	s_add_i32 m0, s9, 0xc000
	ds_read_b128 v[180:183], v150
	ds_read_b128 v[184:187], v150 offset:1024
	ds_read_b128 v[188:191], v150 offset:2048
	ds_read_b128 v[192:195], v150 offset:3072
	ds_read_b128 v[196:199], v150 offset:4096
	ds_read_b128 v[200:203], v150 offset:5120
	ds_read_b128 v[204:207], v150 offset:6144
	ds_read_b128 v[208:211], v150 offset:7168
	global_load_lds_dwordx4 v144, s[22:23]
	s_add_i32 m0, s9, 0xe000
	s_nop 0
	global_load_lds_dwordx4 v146, s[22:23]
	s_waitcnt vmcnt(8)
	s_waitcnt lgkmcnt(0)
	v_mfma_f32_16x16x32_bf16 v[132:135], v[36:39], v[180:183], v[132:135]
	v_mfma_f32_16x16x32_bf16 v[132:135], v[152:155], v[184:187], v[132:135]
	v_mfma_f32_16x16x32_bf16 v[128:131], v[160:163], v[184:187], v[128:131]
	v_mfma_f32_16x16x32_bf16 v[128:131], v[156:159], v[180:183], v[128:131]
	s_barrier
	s_setprio 1
	v_mfma_f32_16x16x32_bf16 v[116:119], v[164:167], v[180:183], v[116:119]
	v_mfma_f32_16x16x32_bf16 v[116:119], v[168:171], v[184:187], v[116:119]
	v_mfma_f32_16x16x32_bf16 v[112:115], v[176:179], v[184:187], v[112:115]
	v_mfma_f32_16x16x32_bf16 v[112:115], v[172:175], v[180:183], v[112:115]
	v_mfma_f32_16x16x32_bf16 v[96:99], v[172:175], v[188:191], v[96:99]
	v_mfma_f32_16x16x32_bf16 v[96:99], v[176:179], v[192:195], v[96:99]
	v_mfma_f32_16x16x32_bf16 v[124:127], v[152:155], v[192:195], v[124:127]
	v_mfma_f32_16x16x32_bf16 v[124:127], v[36:39], v[188:191], v[124:127]
	v_mfma_f32_16x16x32_bf16 v[120:123], v[156:159], v[188:191], v[120:123]
	v_mfma_f32_16x16x32_bf16 v[120:123], v[160:163], v[192:195], v[120:123]
	v_mfma_f32_16x16x32_bf16 v[100:103], v[168:171], v[192:195], v[100:103]
	v_mfma_f32_16x16x32_bf16 v[100:103], v[164:167], v[188:191], v[100:103]
	s_setprio 0
	s_setprio 1
	v_mfma_f32_16x16x32_bf16 v[84:87], v[164:167], v[196:199], v[84:87]
	v_mfma_f32_16x16x32_bf16 v[84:87], v[168:171], v[200:203], v[84:87]
	v_mfma_f32_16x16x32_bf16 v[108:111], v[152:155], v[200:203], v[108:111]
	v_mfma_f32_16x16x32_bf16 v[108:111], v[36:39], v[196:199], v[108:111]
	v_mfma_f32_16x16x32_bf16 v[104:107], v[156:159], v[196:199], v[104:107]
	v_mfma_f32_16x16x32_bf16 v[104:107], v[160:163], v[200:203], v[104:107]
	v_mfma_f32_16x16x32_bf16 v[80:83], v[176:179], v[200:203], v[80:83]
	v_mfma_f32_16x16x32_bf16 v[80:83], v[172:175], v[196:199], v[80:83]
	v_mfma_f32_16x16x32_bf16 v[72:75], v[172:175], v[204:207], v[72:75]
	v_mfma_f32_16x16x32_bf16 v[72:75], v[176:179], v[208:211], v[72:75]
	v_mfma_f32_16x16x32_bf16 v[92:95], v[152:155], v[208:211], v[92:95]
	v_mfma_f32_16x16x32_bf16 v[92:95], v[36:39], v[204:207], v[92:95]
	v_mfma_f32_16x16x32_bf16 v[88:91], v[156:159], v[204:207], v[88:91]
	v_mfma_f32_16x16x32_bf16 v[88:91], v[160:163], v[208:211], v[88:91]
	v_mfma_f32_16x16x32_bf16 v[76:79], v[168:171], v[208:211], v[76:79]
	v_mfma_f32_16x16x32_bf16 v[76:79], v[164:167], v[204:207], v[76:79]
	s_setprio 0
	s_barrier
	s_add_i32 s68, s68, s34
	s_mov_b32 m0, s68
	ds_read_b128 v[180:183], v150 offset:16384
	ds_read_b128 v[184:187], v150 offset:17408
	ds_read_b128 v[188:191], v150 offset:18432
	ds_read_b128 v[192:195], v150 offset:19456
	ds_read_b128 v[196:199], v150 offset:20480
	ds_read_b128 v[200:203], v150 offset:21504
	ds_read_b128 v[204:207], v150 offset:22528
	ds_read_b128 v[208:211], v150 offset:23552
	global_load_lds_dwordx4 v138, s[26:27]
	s_add_i32 m0, s68, 0x2000
	s_add_u32 s68, s26, 0x4000
	s_addc_u32 s69, s27, 0
	s_add_i32 s88, s88, s34
	global_load_lds_dwordx4 v142, s[26:27]
	s_mov_b32 m0, s88
	s_nop 0
	global_load_lds_dwordx4 v138, s[68:69]
	s_add_i32 m0, s88, 0x2000
	s_nop 0
	global_load_lds_dwordx4 v142, s[68:69]
	s_mov_b32 m0, s9
	s_nop 0
	global_load_lds_dwordx4 v136, s[28:29]
	s_mov_b32 m0, s35
	s_nop 0
	global_load_lds_dwordx4 v140, s[28:29]
	s_waitcnt vmcnt(8)
	s_waitcnt lgkmcnt(0)
	v_mfma_f32_16x16x32_bf16 v[68:71], v[36:39], v[180:183], v[68:71]
	v_mfma_f32_16x16x32_bf16 v[68:71], v[152:155], v[184:187], v[68:71]
	v_mfma_f32_16x16x32_bf16 v[64:67], v[160:163], v[184:187], v[64:67]
	v_mfma_f32_16x16x32_bf16 v[64:67], v[156:159], v[180:183], v[64:67]
	s_barrier
; #define PG8_STAGE(bufoff, gbase, voff) do { _Pragma("unroll") for (int _i = 0; _i < 2; ++_i) \
;         __builtin_amdgcn_global_load_lds((const unsigned*)((const char*)(gbase) + (voff)[_i]), (PG8_LAS unsigned*)(lds + (bufoff) + ldsw + _i * 8192), 16, 0, 0); } while (0)
; #define PG8_LDA(dst, b, h) do { _Pragma("unroll") for (int m = 0; m < 4; ++m) _Pragma("unroll") for (int k = 0; k < 2; ++k) dst[m][k] = *(const PG8_LAS bf16x8*)(lds + PG8_SA(b, h) + aoff + m * 2048 + k * 1024); } while (0)
; #define PG8_LDB(dst, b, h) do { _Pragma("unroll") for (int n = 0; n < 2; ++n) _Pragma("unroll") for (int k = 0; k < 2; ++k) dst[n][k] = *(const PG8_LAS bf16x8*)(lds + PG8_SB(b, h) + boff + n * 2048 + k * 1024); } while (0)
; #define PG8_MMA(ai, bj, At, Bt) do { __builtin_amdgcn_s_setprio(1); _Pragma("unroll") for (int m = 0; m < 4; ++m) _Pragma("unroll") for (int n = 0; n < 2; ++n) _Pragma("unroll") for (int k = 0; k < 2; ++k) \
;         acc[ai][bj][m][n] = __builtin_amdgcn_mfma_f32_16x16x32_bf16(Bt[n][k], At[m][k], acc[ai][bj][m][n], 0, 0, 0); __builtin_amdgcn_s_setprio(0); } while (0)
; #define PG8_WAIT_V(n) asm volatile("s_waitcnt vmcnt(" #n ")" ::: "memory")
; #define PG8_WAIT_L(n) asm volatile("s_waitcnt lgkmcnt(" #n ")" ::: "memory")
; #define PG8_BAR __builtin_amdgcn_s_barrier()
; #define PG8_SCHED __builtin_amdgcn_sched_barrier(0)
; template <class Epi, class Sched, bool ALIGN_EPI = false, bool SP2 = false, bool ABLK = false, bool BBLK = false>
; __device__ __forceinline__ void gemm_phase(PG8_LAS unsigned char* lds, const Gemm g, const Sched& S, const Epi& E) {
;     ...
;             PG8_WAIT_V(8); PG8_WAIT_L(0); PG8_BAR; PG8_MMA(1, 0, At, B0); PG8_MMA(1, 1, At, B1); PG8_BAR; PG8_SCHED;
;             PG8_LDB(B0, 1, 0); PG8_LDB(B1, 1, 1); PG8_SCHED; PG8_LDA(At, 1, 0); PG8_STAGE(PG8_SA(0, 1), a2 + hstepA, voffA);
;             PG8_WAIT_V(8); PG8_WAIT_L(0); PG8_BAR; PG8_MMA(0, 0, At, B0); PG8_MMA(0, 1, At, B1); PG8_BAR; PG8_SCHED;
	s_setprio 1
	v_mfma_f32_16x16x32_bf16 v[56:59], v[156:159], v[188:191], v[56:59]
	v_mfma_f32_16x16x32_bf16 v[56:59], v[160:163], v[192:195], v[56:59]
	v_mfma_f32_16x16x32_bf16 v[60:63], v[152:155], v[192:195], v[60:63]
	v_mfma_f32_16x16x32_bf16 v[60:63], v[36:39], v[188:191], v[60:63]
	v_mfma_f32_16x16x32_bf16 v[44:47], v[36:39], v[196:199], v[44:47]
	v_mfma_f32_16x16x32_bf16 v[44:47], v[152:155], v[200:203], v[44:47]
	v_mfma_f32_16x16x32_bf16 v[40:43], v[160:163], v[200:203], v[40:43]
	v_mfma_f32_16x16x32_bf16 v[40:43], v[156:159], v[196:199], v[40:43]
	v_mfma_f32_16x16x32_bf16 v[20:23], v[156:159], v[204:207], v[20:23]
	v_mfma_f32_16x16x32_bf16 v[20:23], v[160:163], v[208:211], v[20:23]
	v_mfma_f32_16x16x32_bf16 v[24:27], v[152:155], v[208:211], v[24:27]
	v_mfma_f32_16x16x32_bf16 v[24:27], v[36:39], v[204:207], v[24:27]
	s_setprio 0
	s_setprio 1
	v_mfma_f32_16x16x32_bf16 v[48:51], v[172:175], v[180:183], v[48:51]
	v_mfma_f32_16x16x32_bf16 v[32:35], v[164:167], v[188:191], v[32:35]
	v_mfma_f32_16x16x32_bf16 v[28:31], v[172:175], v[188:191], v[28:31]
	v_mfma_f32_16x16x32_bf16 v[16:19], v[164:167], v[196:199], v[16:19]
	v_mfma_f32_16x16x32_bf16 v[12:15], v[172:175], v[196:199], v[12:15]
	v_mfma_f32_16x16x32_bf16 v[8:11], v[164:167], v[204:207], v[8:11]
	v_mfma_f32_16x16x32_bf16 v[4:7], v[172:175], v[204:207], v[4:7]
	v_mfma_f32_16x16x32_bf16 v[36:39], v[164:167], v[180:183], v[52:55]
	v_mfma_f32_16x16x32_bf16 v[48:51], v[176:179], v[184:187], v[48:51]
	v_mfma_f32_16x16x32_bf16 v[32:35], v[168:171], v[192:195], v[32:35]
	v_mfma_f32_16x16x32_bf16 v[28:31], v[176:179], v[192:195], v[28:31]
	v_mfma_f32_16x16x32_bf16 v[16:19], v[168:171], v[200:203], v[16:19]
	v_mfma_f32_16x16x32_bf16 v[12:15], v[176:179], v[200:203], v[12:15]
	v_mfma_f32_16x16x32_bf16 v[8:11], v[168:171], v[208:211], v[8:11]
	v_mfma_f32_16x16x32_bf16 v[4:7], v[176:179], v[208:211], v[4:7]
	v_mfma_f32_16x16x32_bf16 v[36:39], v[168:171], v[184:187], v[36:39]
	s_setprio 0
	s_barrier
	s_add_i32 s68, 0, 0x18000
	v_add_u32_e32 v151, s68, v148
	s_add_i32 s69, 0, 0x1c000
	ds_read_b128 v[52:55], v151
	ds_read_b128 v[152:155], v151 offset:1024
	ds_read_b128 v[156:159], v151 offset:2048
	ds_read_b128 v[160:163], v151 offset:3072
	v_add_u32_e32 v151, s69, v148
	ds_read_b128 v[164:167], v151
	ds_read_b128 v[168:171], v151 offset:1024
	ds_read_b128 v[172:175], v151 offset:2048
	ds_read_b128 v[176:179], v151 offset:3072
	s_add_u32 s28, s28, 0x4000
	s_addc_u32 s29, s29, 0
	s_mov_b32 m0, s36
	ds_read_b128 v[180:183], v150 offset:32768
	ds_read_b128 v[184:187], v150 offset:33792
	ds_read_b128 v[188:191], v150 offset:34816
	ds_read_b128 v[192:195], v150 offset:35840
	ds_read_b128 v[196:199], v150 offset:36864
	ds_read_b128 v[200:203], v150 offset:37888
	ds_read_b128 v[204:207], v150 offset:38912
	ds_read_b128 v[208:211], v150 offset:39936
	global_load_lds_dwordx4 v136, s[28:29]
	s_mov_b32 m0, s37
	s_nop 0
	global_load_lds_dwordx4 v140, s[28:29]
	s_waitcnt vmcnt(8)
	s_waitcnt lgkmcnt(0)
	v_mfma_f32_16x16x32_bf16 v[132:135], v[52:55], v[180:183], v[132:135]
	v_mfma_f32_16x16x32_bf16 v[132:135], v[152:155], v[184:187], v[132:135]
	v_mfma_f32_16x16x32_bf16 v[128:131], v[160:163], v[184:187], v[128:131]
	v_mfma_f32_16x16x32_bf16 v[128:131], v[156:159], v[180:183], v[128:131]
	s_barrier
	s_setprio 1
	v_mfma_f32_16x16x32_bf16 v[116:119], v[164:167], v[180:183], v[116:119]
	v_mfma_f32_16x16x32_bf16 v[116:119], v[168:171], v[184:187], v[116:119]
	v_mfma_f32_16x16x32_bf16 v[112:115], v[176:179], v[184:187], v[112:115]
	v_mfma_f32_16x16x32_bf16 v[112:115], v[172:175], v[180:183], v[112:115]
	v_mfma_f32_16x16x32_bf16 v[96:99], v[172:175], v[188:191], v[96:99]
	v_mfma_f32_16x16x32_bf16 v[96:99], v[176:179], v[192:195], v[96:99]
	v_mfma_f32_16x16x32_bf16 v[124:127], v[152:155], v[192:195], v[124:127]
	v_mfma_f32_16x16x32_bf16 v[124:127], v[52:55], v[188:191], v[124:127]
	v_mfma_f32_16x16x32_bf16 v[120:123], v[156:159], v[188:191], v[120:123]
	v_mfma_f32_16x16x32_bf16 v[120:123], v[160:163], v[192:195], v[120:123]
	v_mfma_f32_16x16x32_bf16 v[100:103], v[168:171], v[192:195], v[100:103]
	v_mfma_f32_16x16x32_bf16 v[100:103], v[164:167], v[188:191], v[100:103]
	s_setprio 0
	s_setprio 1
	v_mfma_f32_16x16x32_bf16 v[84:87], v[164:167], v[196:199], v[84:87]
	v_mfma_f32_16x16x32_bf16 v[84:87], v[168:171], v[200:203], v[84:87]
	v_mfma_f32_16x16x32_bf16 v[108:111], v[152:155], v[200:203], v[108:111]
	v_mfma_f32_16x16x32_bf16 v[108:111], v[52:55], v[196:199], v[108:111]
	v_mfma_f32_16x16x32_bf16 v[104:107], v[156:159], v[196:199], v[104:107]
	v_mfma_f32_16x16x32_bf16 v[104:107], v[160:163], v[200:203], v[104:107]
	v_mfma_f32_16x16x32_bf16 v[80:83], v[176:179], v[200:203], v[80:83]
	v_mfma_f32_16x16x32_bf16 v[80:83], v[172:175], v[196:199], v[80:83]
	v_mfma_f32_16x16x32_bf16 v[72:75], v[172:175], v[204:207], v[72:75]
	v_mfma_f32_16x16x32_bf16 v[72:75], v[176:179], v[208:211], v[72:75]
	v_mfma_f32_16x16x32_bf16 v[92:95], v[152:155], v[208:211], v[92:95]
	v_mfma_f32_16x16x32_bf16 v[92:95], v[52:55], v[204:207], v[92:95]
	v_mfma_f32_16x16x32_bf16 v[88:91], v[156:159], v[204:207], v[88:91]
	v_mfma_f32_16x16x32_bf16 v[88:91], v[160:163], v[208:211], v[88:91]
	v_mfma_f32_16x16x32_bf16 v[76:79], v[168:171], v[208:211], v[76:79]
	v_mfma_f32_16x16x32_bf16 v[76:79], v[164:167], v[204:207], v[76:79]
	s_setprio 0
	s_barrier
; #define PG8_STAGE(bufoff, gbase, voff) do { _Pragma("unroll") for (int _i = 0; _i < 2; ++_i) \
;         __builtin_amdgcn_global_load_lds((const unsigned*)((const char*)(gbase) + (voff)[_i]), (PG8_LAS unsigned*)(lds + (bufoff) + ldsw + _i * 8192), 16, 0, 0); } while (0)
; #define PG8_LDA(dst, b, h) do { _Pragma("unroll") for (int m = 0; m < 4; ++m) _Pragma("unroll") for (int k = 0; k < 2; ++k) dst[m][k] = *(const PG8_LAS bf16x8*)(lds + PG8_SA(b, h) + aoff + m * 2048 + k * 1024); } while (0)
; #define PG8_MMA(ai, bj, At, Bt) do { __builtin_amdgcn_s_setprio(1); _Pragma("unroll") for (int m = 0; m < 4; ++m) _Pragma("unroll") for (int n = 0; n < 2; ++n) _Pragma("unroll") for (int k = 0; k < 2; ++k) \
;         acc[ai][bj][m][n] = __builtin_amdgcn_mfma_f32_16x16x32_bf16(Bt[n][k], At[m][k], acc[ai][bj][m][n], 0, 0, 0); __builtin_amdgcn_s_setprio(0); } while (0)
; #define PG8_WAIT_V(n) asm volatile("s_waitcnt vmcnt(" #n ")" ::: "memory")
; #define PG8_WAIT_L(n) asm volatile("s_waitcnt lgkmcnt(" #n ")" ::: "memory")
; #define PG8_BAR __builtin_amdgcn_s_barrier()
; #define PG8_SCHED __builtin_amdgcn_sched_barrier(0)
; template <class Epi, class Sched, bool ALIGN_EPI = false, bool SP2 = false, bool ABLK = false, bool BBLK = false>
; __device__ __forceinline__ void gemm_phase(PG8_LAS unsigned char* lds, const Gemm g, const Sched& S, const Epi& E) {
;     ...
;         for (int t = 0; t < nt; t += 2) {
;             const bool last = (t == nt - 2);
;     ...
;             PG8_LDA(At, 1, 1); PG8_STAGE(PG8_SB(1, 0), b3, voffB); PG8_STAGE(PG8_SB(1, 1), b3 + hstepB, voffB); PG8_STAGE(PG8_SA(1, 0), a3, voffA);
;             PG8_WAIT_V(8); PG8_WAIT_L(0); PG8_BAR; PG8_MMA(1, 0, At, B0); PG8_MMA(1, 1, At, B1); PG8_BAR; PG8_SCHED;
	s_add_u32 s28, s26, 0x8000
	s_addc_u32 s29, s27, 0
	s_add_i32 s68, s68, s34
	s_mov_b32 m0, s68
	ds_read_b128 v[180:183], v150 offset:49152
	ds_read_b128 v[184:187], v150 offset:50176
	ds_read_b128 v[188:191], v150 offset:51200
	ds_read_b128 v[192:195], v150 offset:52224
	ds_read_b128 v[196:199], v150 offset:53248
	ds_read_b128 v[200:203], v150 offset:54272
	ds_read_b128 v[204:207], v150 offset:55296
	ds_read_b128 v[208:211], v150 offset:56320
	global_load_lds_dwordx4 v138, s[28:29]
	s_add_i32 m0, s68, 0x2000
	s_add_u32 s26, s26, 0xc000
	s_addc_u32 s27, s27, 0
	global_load_lds_dwordx4 v142, s[28:29]
	s_add_i32 s28, s69, s34
	s_mov_b32 m0, s28
	s_nop 0
	global_load_lds_dwordx4 v138, s[26:27]
	s_add_i32 m0, s28, 0x2000
	s_nop 0
	global_load_lds_dwordx4 v142, s[26:27]
	s_mov_b32 m0, s64
	s_nop 0
	global_load_lds_dwordx4 v136, s[24:25]
	s_mov_b32 m0, s65
	s_nop 0
	global_load_lds_dwordx4 v140, s[24:25]
	s_waitcnt vmcnt(8)
	s_waitcnt lgkmcnt(0)
	v_mfma_f32_16x16x32_bf16 v[68:71], v[52:55], v[180:183], v[68:71]
	v_mfma_f32_16x16x32_bf16 v[68:71], v[152:155], v[184:187], v[68:71]
	v_mfma_f32_16x16x32_bf16 v[64:67], v[160:163], v[184:187], v[64:67]
	v_mfma_f32_16x16x32_bf16 v[64:67], v[156:159], v[180:183], v[64:67]
	s_barrier
	s_setprio 1
	v_mfma_f32_16x16x32_bf16 v[56:59], v[156:159], v[188:191], v[56:59]
	v_mfma_f32_16x16x32_bf16 v[56:59], v[160:163], v[192:195], v[56:59]
	v_mfma_f32_16x16x32_bf16 v[60:63], v[152:155], v[192:195], v[60:63]
	v_mfma_f32_16x16x32_bf16 v[60:63], v[52:55], v[188:191], v[60:63]
	v_mfma_f32_16x16x32_bf16 v[44:47], v[52:55], v[196:199], v[44:47]
	v_mfma_f32_16x16x32_bf16 v[44:47], v[152:155], v[200:203], v[44:47]
	v_mfma_f32_16x16x32_bf16 v[40:43], v[160:163], v[200:203], v[40:43]
	v_mfma_f32_16x16x32_bf16 v[40:43], v[156:159], v[196:199], v[40:43]
	v_mfma_f32_16x16x32_bf16 v[20:23], v[156:159], v[204:207], v[20:23]
	v_mfma_f32_16x16x32_bf16 v[20:23], v[160:163], v[208:211], v[20:23]
	v_mfma_f32_16x16x32_bf16 v[24:27], v[152:155], v[208:211], v[24:27]
	v_mfma_f32_16x16x32_bf16 v[24:27], v[52:55], v[204:207], v[24:27]
	s_setprio 0
	s_setprio 1
	v_mfma_f32_16x16x32_bf16 v[36:39], v[164:167], v[180:183], v[36:39]
	v_mfma_f32_16x16x32_bf16 v[52:55], v[168:171], v[184:187], v[36:39]
	v_mfma_f32_16x16x32_bf16 v[36:39], v[172:175], v[180:183], v[48:51]
	v_mfma_f32_16x16x32_bf16 v[32:35], v[164:167], v[188:191], v[32:35]
	v_mfma_f32_16x16x32_bf16 v[28:31], v[172:175], v[188:191], v[28:31]
	v_mfma_f32_16x16x32_bf16 v[16:19], v[164:167], v[196:199], v[16:19]
	v_mfma_f32_16x16x32_bf16 v[12:15], v[172:175], v[196:199], v[12:15]
	v_mfma_f32_16x16x32_bf16 v[8:11], v[164:167], v[204:207], v[8:11]
	v_mfma_f32_16x16x32_bf16 v[4:7], v[172:175], v[204:207], v[4:7]
	v_mfma_f32_16x16x32_bf16 v[48:51], v[176:179], v[184:187], v[36:39]
	v_mfma_f32_16x16x32_bf16 v[32:35], v[168:171], v[192:195], v[32:35]
	v_mfma_f32_16x16x32_bf16 v[28:31], v[176:179], v[192:195], v[28:31]
	v_mfma_f32_16x16x32_bf16 v[16:19], v[168:171], v[200:203], v[16:19]
	v_mfma_f32_16x16x32_bf16 v[12:15], v[176:179], v[200:203], v[12:15]
	v_mfma_f32_16x16x32_bf16 v[8:11], v[168:171], v[208:211], v[8:11]
	v_mfma_f32_16x16x32_bf16 v[4:7], v[176:179], v[208:211], v[4:7]
	s_setprio 0
	s_barrier
	s_add_i32 s13, s13, 2
	s_add_u32 s22, s22, 0x10000
	s_addc_u32 s23, s23, 0
	s_add_u32 s82, s82, 0x10000
	s_addc_u32 vcc_lo, vcc_lo, 0
	s_cmp_gt_u32 s13, 29
	s_cbranch_scc0 .LBB0_2111
	s_and_b64 vcc, exec, s[6:7]
	s_movk_i32 s77, 0x1000
	s_cbranch_vccz .LBB0_2114
	s_barrier
